# speedup vs baseline: 1.0114x; 1.0114x over previous
; #define G_STAGE(bufoff, gbase, voff) do { _Pragma("unroll") for (int _i = 0; _i < 2; ++_i) \
;         __builtin_amdgcn_global_load_lds((const unsigned*)((const char*)(gbase) + (voff)[_i]), (LAS unsigned*)(lds + (bufoff) + ldsw + _i * 8192), 16, 0, 0); } while (0)
; #define G_LDA(dst, b, h) do { _Pragma("unroll") for (int m = 0; m < 4; ++m) _Pragma("unroll") for (int k = 0; k < 2; ++k) dst[m][k] = *(const LAS bf16x8*)(lds + G_SA(b, h) + aoff + m * 2048 + k * 1024); } while (0)
; #define G_LDB(dst, b, h) do { _Pragma("unroll") for (int n = 0; n < 2; ++n) _Pragma("unroll") for (int k = 0; k < 2; ++k) dst[n][k] = *(const LAS bf16x8*)(lds + G_SB(b, h) + boff + n * 2048 + k * 1024); } while (0)
; #define G_MMA(ai, bj, At, Bt) do { __builtin_amdgcn_s_setprio(1); _Pragma("unroll") for (int m = 0; m < 4; ++m) _Pragma("unroll") for (int n = 0; n < 2; ++n) _Pragma("unroll") for (int k = 0; k < 2; ++k) \
;         acc[ai][bj][m][n] = __builtin_amdgcn_mfma_f32_16x16x32_bf16(Bt[n][k], At[m][k], acc[ai][bj][m][n], 0, 0, 0); __builtin_amdgcn_s_setprio(0); } while (0)
; #define G_WAIT_V(n) asm volatile("s_waitcnt vmcnt(" #n ")" ::: "memory")
; #define G_WAIT_L(n) asm volatile("s_waitcnt lgkmcnt(" #n ")" ::: "memory")
; #define G_BAR __builtin_amdgcn_s_barrier()
; #define G_SCHED __builtin_amdgcn_sched_barrier(0)
; template <class J>
; DI void gemm_phase(LAS unsigned char* lds, const J& job) {
;     ...
;       G_LDB(B0, 0, 0); G_SCHED; G_LDA(At, 0, 0); G_STAGE(G_SA(1, 1), a1 + hstepA, voffA);
;       G_WAIT_L(8); G_BAR; G_WAIT_L(0); G_MMA(0, 0, At, B0); G_BAR; G_SCHED;
;       G_LDB(B1, 0, 1); G_STAGE(G_SB(0, 0), b2, voffB);
;       G_BAR; G_WAIT_L(0); G_MMA(0, 1, At, B1); G_BAR;
;       G_LDA(At, 0, 1); G_STAGE(G_SA(0, 0), a2, voffA);
;       G_BAR; G_WAIT_L(0); G_MMA(1, 0, At, B0); G_BAR; G_SCHED;
;       G_STAGE(G_SB(0, 1), b2 + hstepB, voffB);
;       G_WAIT_V(6); G_BAR; G_MMA(1, 1, At, B1); G_BAR;
.LBB0_42:
	s_add_i32 s2, s84, 0x100
	ds_read_b128 v[128:131], v221
	ds_read_b128 v[132:135], v221 offset:1024
	ds_read_b128 v[136:139], v221 offset:2048
	ds_read_b128 v[140:143], v221 offset:3072
	s_add_u32 s0, s21, s0
	s_addc_u32 s1, s23, 0
	s_add_i32 m0, s25, 0xc000
	ds_read_b128 v[154:157], v163
	ds_read_b128 v[164:167], v163 offset:1024
	ds_read_b128 v[168:171], v163 offset:2048
	ds_read_b128 v[172:175], v163 offset:3072
	ds_read_b128 v[176:179], v163 offset:4096
	ds_read_b128 v[180:183], v163 offset:5120
	ds_read_b128 v[184:187], v163 offset:6144
	ds_read_b128 v[188:191], v163 offset:7168
	global_load_lds_dwordx4 v148, s[0:1]
	s_add_i32 m0, s25, 0xe000
	s_nop 0
	global_load_lds_dwordx4 v150, s[0:1]
	s_waitcnt lgkmcnt(8)
	s_barrier
	s_waitcnt lgkmcnt(0)
	v_mfma_f32_16x16x32_bf16 v[124:127], v[128:131], v[154:157], v[124:127]
	v_mfma_f32_16x16x32_bf16 v[120:123], v[136:139], v[154:157], v[120:123]
	v_mfma_f32_16x16x32_bf16 v[108:111], v[128:131], v[168:171], v[108:111]
	v_mfma_f32_16x16x32_bf16 v[104:107], v[136:139], v[168:171], v[104:107]
	v_mfma_f32_16x16x32_bf16 v[92:95], v[128:131], v[176:179], v[92:95]
	v_mfma_f32_16x16x32_bf16 v[88:91], v[136:139], v[176:179], v[88:91]
	v_mfma_f32_16x16x32_bf16 v[76:79], v[128:131], v[184:187], v[76:79]
	v_mfma_f32_16x16x32_bf16 v[72:75], v[136:139], v[184:187], v[72:75]
	v_mfma_f32_16x16x32_bf16 v[124:127], v[132:135], v[164:167], v[124:127]
	v_mfma_f32_16x16x32_bf16 v[120:123], v[140:143], v[164:167], v[120:123]
	v_mfma_f32_16x16x32_bf16 v[108:111], v[132:135], v[172:175], v[108:111]
	v_mfma_f32_16x16x32_bf16 v[104:107], v[140:143], v[172:175], v[104:107]
	v_mfma_f32_16x16x32_bf16 v[92:95], v[132:135], v[180:183], v[92:95]
	v_mfma_f32_16x16x32_bf16 v[88:91], v[140:143], v[180:183], v[88:91]
	v_mfma_f32_16x16x32_bf16 v[76:79], v[132:135], v[188:191], v[76:79]
	v_mfma_f32_16x16x32_bf16 v[72:75], v[140:143], v[188:191], v[72:75]
	s_barrier
	s_add_i32 s54, s85, 0x100
	s_add_i32 s0, s2, s14
	ds_read_b128 v[192:195], v221 offset:16384
	ds_read_b128 v[196:199], v221 offset:17408
	ds_read_b128 v[200:203], v221 offset:18432
	ds_read_b128 v[204:207], v221 offset:19456
	s_mov_b32 m0, s0
	s_nop 0
	global_load_lds_dwordx4 v146, s[78:79]
	s_add_i32 m0, s0, 0x2000
	s_nop 0
	global_load_lds_dwordx4 v152, s[78:79]
	s_barrier
	s_waitcnt lgkmcnt(0)
	v_mfma_f32_16x16x32_bf16 v[116:119], v[192:195], v[154:157], v[116:119]
	v_mfma_f32_16x16x32_bf16 v[112:115], v[200:203], v[154:157], v[112:115]
	v_mfma_f32_16x16x32_bf16 v[100:103], v[192:195], v[168:171], v[100:103]
	v_mfma_f32_16x16x32_bf16 v[96:99], v[200:203], v[168:171], v[96:99]
	v_mfma_f32_16x16x32_bf16 v[84:87], v[192:195], v[176:179], v[84:87]
	v_mfma_f32_16x16x32_bf16 v[80:83], v[200:203], v[176:179], v[80:83]
	v_mfma_f32_16x16x32_bf16 v[68:71], v[192:195], v[184:187], v[68:71]
	v_mfma_f32_16x16x32_bf16 v[64:67], v[200:203], v[184:187], v[64:67]
	v_mfma_f32_16x16x32_bf16 v[116:119], v[196:199], v[164:167], v[116:119]
	v_mfma_f32_16x16x32_bf16 v[112:115], v[204:207], v[164:167], v[112:115]
	v_mfma_f32_16x16x32_bf16 v[100:103], v[196:199], v[172:175], v[100:103]
	v_mfma_f32_16x16x32_bf16 v[96:99], v[204:207], v[172:175], v[96:99]
	v_mfma_f32_16x16x32_bf16 v[84:87], v[196:199], v[180:183], v[84:87]
	v_mfma_f32_16x16x32_bf16 v[80:83], v[204:207], v[180:183], v[80:83]
	v_mfma_f32_16x16x32_bf16 v[68:71], v[196:199], v[188:191], v[68:71]
	v_mfma_f32_16x16x32_bf16 v[64:67], v[204:207], v[188:191], v[64:67]
	s_mov_b32 m0, s25
	s_barrier
	ds_read_b128 v[154:157], v163 offset:16384
	ds_read_b128 v[164:167], v163 offset:17408
	ds_read_b128 v[168:171], v163 offset:18432
	ds_read_b128 v[172:175], v163 offset:19456
	ds_read_b128 v[176:179], v163 offset:20480
	ds_read_b128 v[180:183], v163 offset:21504
	ds_read_b128 v[184:187], v163 offset:22528
	ds_read_b128 v[188:191], v163 offset:23552
	global_load_lds_dwordx4 v148, s[76:77]
	s_mov_b32 m0, s36
	s_nop 0
	global_load_lds_dwordx4 v150, s[76:77]
	s_barrier
	s_waitcnt lgkmcnt(0)
	v_mfma_f32_16x16x32_bf16 v[60:63], v[128:131], v[154:157], v[60:63]
	v_mfma_f32_16x16x32_bf16 v[56:59], v[136:139], v[154:157], v[56:59]
	v_mfma_f32_16x16x32_bf16 v[44:47], v[128:131], v[168:171], v[44:47]
	v_mfma_f32_16x16x32_bf16 v[40:43], v[136:139], v[168:171], v[40:43]
	v_mfma_f32_16x16x32_bf16 v[28:31], v[128:131], v[176:179], v[28:31]
	v_mfma_f32_16x16x32_bf16 v[24:27], v[136:139], v[176:179], v[24:27]
	v_mfma_f32_16x16x32_bf16 v[20:23], v[128:131], v[184:187], v[20:23]
	v_mfma_f32_16x16x32_bf16 v[12:15], v[136:139], v[184:187], v[12:15]
	v_mfma_f32_16x16x32_bf16 v[60:63], v[132:135], v[164:167], v[60:63]
	v_mfma_f32_16x16x32_bf16 v[56:59], v[140:143], v[164:167], v[56:59]
	v_mfma_f32_16x16x32_bf16 v[44:47], v[132:135], v[172:175], v[44:47]
	v_mfma_f32_16x16x32_bf16 v[40:43], v[140:143], v[172:175], v[40:43]
	v_mfma_f32_16x16x32_bf16 v[28:31], v[132:135], v[180:183], v[28:31]
	v_mfma_f32_16x16x32_bf16 v[24:27], v[140:143], v[180:183], v[24:27]
	v_mfma_f32_16x16x32_bf16 v[20:23], v[132:135], v[188:191], v[20:23]
	v_mfma_f32_16x16x32_bf16 v[12:15], v[140:143], v[188:191], v[12:15]
	s_barrier
	s_add_u32 s0, s78, 0x80000
	s_addc_u32 s1, s79, 0
	s_add_i32 s2, s54, s14
	s_mov_b32 m0, s2
	s_nop 0
	global_load_lds_dwordx4 v146, s[0:1]
	s_add_i32 m0, s2, 0x2000
	s_nop 0
	global_load_lds_dwordx4 v152, s[0:1]
	s_waitcnt vmcnt(6)
	s_barrier
; #define G_STAGE(bufoff, gbase, voff) do { _Pragma("unroll") for (int _i = 0; _i < 2; ++_i) \
;         __builtin_amdgcn_global_load_lds((const unsigned*)((const char*)(gbase) + (voff)[_i]), (LAS unsigned*)(lds + (bufoff) + ldsw + _i * 8192), 16, 0, 0); } while (0)
; #define G_LDA(dst, b, h) do { _Pragma("unroll") for (int m = 0; m < 4; ++m) _Pragma("unroll") for (int k = 0; k < 2; ++k) dst[m][k] = *(const LAS bf16x8*)(lds + G_SA(b, h) + aoff + m * 2048 + k * 1024); } while (0)
; #define G_LDB(dst, b, h) do { _Pragma("unroll") for (int n = 0; n < 2; ++n) _Pragma("unroll") for (int k = 0; k < 2; ++k) dst[n][k] = *(const LAS bf16x8*)(lds + G_SB(b, h) + boff + n * 2048 + k * 1024); } while (0)
; #define G_MMA(ai, bj, At, Bt) do { __builtin_amdgcn_s_setprio(1); _Pragma("unroll") for (int m = 0; m < 4; ++m) _Pragma("unroll") for (int n = 0; n < 2; ++n) _Pragma("unroll") for (int k = 0; k < 2; ++k) \
;         acc[ai][bj][m][n] = __builtin_amdgcn_mfma_f32_16x16x32_bf16(Bt[n][k], At[m][k], acc[ai][bj][m][n], 0, 0, 0); __builtin_amdgcn_s_setprio(0); } while (0)
; #define G_WAIT_V(n) asm volatile("s_waitcnt vmcnt(" #n ")" ::: "memory")
; #define G_WAIT_L(n) asm volatile("s_waitcnt lgkmcnt(" #n ")" ::: "memory")
; #define G_BAR __builtin_amdgcn_s_barrier()
; #define G_SCHED __builtin_amdgcn_sched_barrier(0)
; template <class J>
; DI void gemm_phase(LAS unsigned char* lds, const J& job) {
;     ...
;       G_WAIT_V(6); G_BAR; G_MMA(1, 1, At, B1); G_BAR;
;       G_LDB(B0, 1, 0); G_SCHED; G_LDA(At, 1, 0); G_STAGE(G_SA(0, 1), a2 + hstepA, voffA);
;       G_WAIT_L(8); G_BAR; G_WAIT_L(0); G_MMA(0, 0, At, B0); G_BAR; G_SCHED;
;       G_LDB(B1, 1, 1); G_STAGE(G_SB(1, 0), b3, voffB);
;       G_BAR; G_WAIT_L(0); G_MMA(0, 1, At, B1); G_BAR;
;       G_LDA(At, 1, 1); G_STAGE(G_SA(1, 0), a3, voffA);
;       G_BAR; G_WAIT_L(0); G_MMA(1, 0, At, B0); G_BAR; G_SCHED;
	v_mfma_f32_16x16x32_bf16 v[52:55], v[192:195], v[154:157], v[52:55]
	v_mfma_f32_16x16x32_bf16 v[48:51], v[200:203], v[154:157], v[48:51]
	v_mfma_f32_16x16x32_bf16 v[36:39], v[192:195], v[168:171], v[36:39]
	v_mfma_f32_16x16x32_bf16 v[32:35], v[200:203], v[168:171], v[32:35]
	v_mfma_f32_16x16x32_bf16 v[16:19], v[192:195], v[176:179], v[16:19]
	v_mfma_f32_16x16x32_bf16 v[8:11], v[200:203], v[176:179], v[8:11]
	v_mfma_f32_16x16x32_bf16 v[4:7], v[192:195], v[184:187], v[4:7]
	v_mfma_f32_16x16x32_bf16 v[0:3], v[200:203], v[184:187], v[0:3]
	v_mfma_f32_16x16x32_bf16 v[52:55], v[196:199], v[164:167], v[52:55]
	v_mfma_f32_16x16x32_bf16 v[48:51], v[204:207], v[164:167], v[48:51]
	v_mfma_f32_16x16x32_bf16 v[36:39], v[196:199], v[172:175], v[36:39]
	v_mfma_f32_16x16x32_bf16 v[32:35], v[204:207], v[172:175], v[32:35]
	v_mfma_f32_16x16x32_bf16 v[16:19], v[196:199], v[180:183], v[16:19]
	v_mfma_f32_16x16x32_bf16 v[8:11], v[204:207], v[180:183], v[8:11]
	v_mfma_f32_16x16x32_bf16 v[4:7], v[196:199], v[188:191], v[4:7]
	v_mfma_f32_16x16x32_bf16 v[0:3], v[204:207], v[188:191], v[0:3]
	s_add_i32 s2, s88, 0x100
	s_barrier
	ds_read_b128 v[128:131], v221 offset:32768
	ds_read_b128 v[132:135], v221 offset:33792
	ds_read_b128 v[136:139], v221 offset:34816
	ds_read_b128 v[140:143], v221 offset:35840
	s_add_u32 s0, s76, 0x80000
	s_addc_u32 s1, s77, 0
	s_mov_b32 m0, s37
	ds_read_b128 v[154:157], v163 offset:32768
	ds_read_b128 v[164:167], v163 offset:33792
	ds_read_b128 v[168:171], v163 offset:34816
	ds_read_b128 v[172:175], v163 offset:35840
	ds_read_b128 v[176:179], v163 offset:36864
	ds_read_b128 v[180:183], v163 offset:37888
	ds_read_b128 v[184:187], v163 offset:38912
	ds_read_b128 v[188:191], v163 offset:39936
	global_load_lds_dwordx4 v148, s[0:1]
	s_mov_b32 m0, s38
	s_nop 0
	global_load_lds_dwordx4 v150, s[0:1]
	s_waitcnt lgkmcnt(8)
	s_barrier
	s_waitcnt lgkmcnt(0)
	v_mfma_f32_16x16x32_bf16 v[124:127], v[128:131], v[154:157], v[124:127]
	v_mfma_f32_16x16x32_bf16 v[120:123], v[136:139], v[154:157], v[120:123]
	v_mfma_f32_16x16x32_bf16 v[108:111], v[128:131], v[168:171], v[108:111]
	v_mfma_f32_16x16x32_bf16 v[104:107], v[136:139], v[168:171], v[104:107]
	v_mfma_f32_16x16x32_bf16 v[92:95], v[128:131], v[176:179], v[92:95]
	v_mfma_f32_16x16x32_bf16 v[88:91], v[136:139], v[176:179], v[88:91]
	v_mfma_f32_16x16x32_bf16 v[76:79], v[128:131], v[184:187], v[76:79]
	v_mfma_f32_16x16x32_bf16 v[72:75], v[136:139], v[184:187], v[72:75]
	v_mfma_f32_16x16x32_bf16 v[124:127], v[132:135], v[164:167], v[124:127]
	v_mfma_f32_16x16x32_bf16 v[120:123], v[140:143], v[164:167], v[120:123]
	v_mfma_f32_16x16x32_bf16 v[108:111], v[132:135], v[172:175], v[108:111]
	v_mfma_f32_16x16x32_bf16 v[104:107], v[140:143], v[172:175], v[104:107]
	v_mfma_f32_16x16x32_bf16 v[92:95], v[132:135], v[180:183], v[92:95]
	v_mfma_f32_16x16x32_bf16 v[88:91], v[140:143], v[180:183], v[88:91]
	v_mfma_f32_16x16x32_bf16 v[76:79], v[132:135], v[188:191], v[76:79]
	v_mfma_f32_16x16x32_bf16 v[72:75], v[140:143], v[188:191], v[72:75]
	s_barrier
	s_add_i32 s54, s89, 0x100
	s_add_i32 s0, s2, s14
	ds_read_b128 v[192:195], v221 offset:49152
	ds_read_b128 v[196:199], v221 offset:50176
	ds_read_b128 v[200:203], v221 offset:51200
	ds_read_b128 v[204:207], v221 offset:52224
	s_mov_b32 m0, s0
	s_nop 0
	global_load_lds_dwordx4 v146, s[72:73]
	s_add_i32 m0, s0, 0x2000
	s_nop 0
	global_load_lds_dwordx4 v152, s[72:73]
	s_barrier
	s_waitcnt lgkmcnt(0)
	v_mfma_f32_16x16x32_bf16 v[116:119], v[192:195], v[154:157], v[116:119]
	v_mfma_f32_16x16x32_bf16 v[112:115], v[200:203], v[154:157], v[112:115]
	v_mfma_f32_16x16x32_bf16 v[100:103], v[192:195], v[168:171], v[100:103]
	v_mfma_f32_16x16x32_bf16 v[96:99], v[200:203], v[168:171], v[96:99]
	v_mfma_f32_16x16x32_bf16 v[84:87], v[192:195], v[176:179], v[84:87]
	v_mfma_f32_16x16x32_bf16 v[80:83], v[200:203], v[176:179], v[80:83]
	v_mfma_f32_16x16x32_bf16 v[68:71], v[192:195], v[184:187], v[68:71]
	v_mfma_f32_16x16x32_bf16 v[64:67], v[200:203], v[184:187], v[64:67]
	v_mfma_f32_16x16x32_bf16 v[116:119], v[196:199], v[164:167], v[116:119]
	v_mfma_f32_16x16x32_bf16 v[112:115], v[204:207], v[164:167], v[112:115]
	v_mfma_f32_16x16x32_bf16 v[100:103], v[196:199], v[172:175], v[100:103]
	v_mfma_f32_16x16x32_bf16 v[96:99], v[204:207], v[172:175], v[96:99]
	v_mfma_f32_16x16x32_bf16 v[84:87], v[196:199], v[180:183], v[84:87]
	v_mfma_f32_16x16x32_bf16 v[80:83], v[204:207], v[180:183], v[80:83]
	v_mfma_f32_16x16x32_bf16 v[68:71], v[196:199], v[188:191], v[68:71]
	v_mfma_f32_16x16x32_bf16 v[64:67], v[204:207], v[188:191], v[64:67]
	s_mov_b32 m0, s87
	s_barrier
	ds_read_b128 v[154:157], v163 offset:49152
	ds_read_b128 v[164:167], v163 offset:50176
	ds_read_b128 v[168:171], v163 offset:51200
	ds_read_b128 v[172:175], v163 offset:52224
	ds_read_b128 v[176:179], v163 offset:53248
	ds_read_b128 v[180:183], v163 offset:54272
	ds_read_b128 v[184:187], v163 offset:55296
	ds_read_b128 v[188:191], v163 offset:56320
	global_load_lds_dwordx4 v148, s[74:75]
	s_mov_b32 m0, s94
	s_nop 0
	global_load_lds_dwordx4 v150, s[74:75]
	s_barrier
; #define G_STAGE(bufoff, gbase, voff) do { _Pragma("unroll") for (int _i = 0; _i < 2; ++_i) \
;         __builtin_amdgcn_global_load_lds((const unsigned*)((const char*)(gbase) + (voff)[_i]), (LAS unsigned*)(lds + (bufoff) + ldsw + _i * 8192), 16, 0, 0); } while (0)
; #define G_WAIT_V(n) asm volatile("s_waitcnt vmcnt(" #n ")" ::: "memory")
; template <class J>
; DI void gemm_phase(LAS unsigned char* lds, const J& job) {
;     ...
;       const bool last = (t == nt - 2);
;       const char* a1 = cA + G_KT(t + 1);
;       const char* a2 = last ? nA + G_KT(0) : cA + G_KT(t + 2); const char* b2 = last ? nB + G_KT(0) : cB + G_KT(t + 2);
;       const char* a3 = last ? nA + G_KT(1) : cA + G_KT(t + 3); const char* b3 = last ? nB + G_KT(1) : cB + G_KT(t + 3);
;       G_LDB(B0, 0, 0); G_SCHED; G_LDA(At, 0, 0); G_STAGE(G_SA(1, 1), a1 + hstepA, voffA);
;       G_WAIT_L(8); G_BAR; G_WAIT_L(0); G_MMA(0, 0, At, B0); G_BAR; G_SCHED;
;       G_LDB(B1, 0, 1); G_STAGE(G_SB(0, 0), b2, voffB);
;       G_BAR; G_WAIT_L(0); G_MMA(0, 1, At, B1); G_BAR;
;       G_LDA(At, 0, 1); G_STAGE(G_SA(0, 0), a2, voffA);
;       G_BAR; G_WAIT_L(0); G_MMA(1, 0, At, B0); G_BAR; G_SCHED;
;       G_STAGE(G_SB(0, 1), b2 + hstepB, voffB);
;       G_WAIT_V(6); G_BAR; G_MMA(1, 1, At, B1); G_BAR;
;       G_LDB(B0, 1, 0); G_SCHED; G_LDA(At, 1, 0); G_STAGE(G_SA(0, 1), a2 + hstepA, voffA);
;       G_WAIT_L(8); G_BAR; G_WAIT_L(0); G_MMA(0, 0, At, B0); G_BAR; G_SCHED;
;       G_LDB(B1, 1, 1); G_STAGE(G_SB(1, 0), b3, voffB);
;       G_BAR; G_WAIT_L(0); G_MMA(0, 1, At, B1); G_BAR;
;       G_LDA(At, 1, 1); G_STAGE(G_SA(1, 0), a3, voffA);
;       G_BAR; G_WAIT_L(0); G_MMA(1, 0, At, B0); G_BAR; G_SCHED;
;       G_STAGE(G_SB(1, 1), b3 + hstepB, voffB);
;       G_WAIT_V(6); G_BAR; G_MMA(1, 1, At, B1); G_BAR;
;   DI void epi(const Acc& acc, const Unit& u, int wr, int wc, int fr, int fq) const {
; #pragma unroll
;     for (int ai = 0; ai < 2; ++ai) {
;       f32x4 res[4][2][2];
; #pragma unroll
;       for (int m = 0; m < 4; ++m) {
;         const int row = u.pm * 256 + ai * HALF + wr * 64 + m * 16 + fr;
;         const float* src = (l == 0) ? xp + (size_t)row * DM : out + (size_t)row * DM;
; #pragma unroll
;         for (int bj = 0; bj < 2; ++bj) { const int col = u.pn * 256 + bj * HALF + wc * 32 + 8 * fq; res[m][bj][0] = *(const f32x4*)(src + col); res[m][bj][1] = *(const f32x4*)(src + col + 4); }
;       }
	s_waitcnt lgkmcnt(0)
	v_mfma_f32_16x16x32_bf16 v[60:63], v[128:131], v[154:157], v[60:63]
	v_mfma_f32_16x16x32_bf16 v[56:59], v[136:139], v[154:157], v[56:59]
	v_mfma_f32_16x16x32_bf16 v[44:47], v[128:131], v[168:171], v[44:47]
	v_mfma_f32_16x16x32_bf16 v[40:43], v[136:139], v[168:171], v[40:43]
	v_mfma_f32_16x16x32_bf16 v[28:31], v[128:131], v[176:179], v[28:31]
	v_mfma_f32_16x16x32_bf16 v[24:27], v[136:139], v[176:179], v[24:27]
	v_mfma_f32_16x16x32_bf16 v[20:23], v[128:131], v[184:187], v[20:23]
	v_mfma_f32_16x16x32_bf16 v[12:15], v[136:139], v[184:187], v[12:15]
	v_mfma_f32_16x16x32_bf16 v[60:63], v[132:135], v[164:167], v[60:63]
	v_mfma_f32_16x16x32_bf16 v[56:59], v[140:143], v[164:167], v[56:59]
	v_mfma_f32_16x16x32_bf16 v[44:47], v[132:135], v[172:175], v[44:47]
	v_mfma_f32_16x16x32_bf16 v[40:43], v[140:143], v[172:175], v[40:43]
	v_mfma_f32_16x16x32_bf16 v[28:31], v[132:135], v[180:183], v[28:31]
	v_mfma_f32_16x16x32_bf16 v[24:27], v[140:143], v[180:183], v[24:27]
	v_mfma_f32_16x16x32_bf16 v[20:23], v[132:135], v[188:191], v[20:23]
	v_mfma_f32_16x16x32_bf16 v[12:15], v[140:143], v[188:191], v[12:15]
	s_barrier
	s_add_u32 s0, s72, 0x80000
	s_addc_u32 s1, s73, 0
	s_add_i32 s2, s54, s14
	s_mov_b32 m0, s2
	s_nop 0
	global_load_lds_dwordx4 v146, s[0:1]
	s_add_i32 m0, s2, 0x2000
	s_nop 0
	global_load_lds_dwordx4 v152, s[0:1]
	s_add_i32 s7, s7, 2
	s_addk_i32 s57, 0x100
	s_addk_i32 s44, 0x100
	s_add_i32 s1, s57, 0xffffff80
	s_and_b32 s0, s44, 0xf80
	s_and_b32 s1, s1, 0xf00
	s_add_u32 s2, s70, s1
	s_addc_u32 s72, s71, 0
	s_add_u32 s1, s68, s1
	s_addc_u32 s73, s69, 0
	s_and_b32 s74, s57, 0xf80
	s_add_u32 s80, s70, s74
	s_addc_u32 s75, s71, 0
	s_add_u32 s54, s68, s74
	s_addc_u32 s55, s69, 0
	s_cmp_eq_u32 s7, 28
	s_cselect_b32 s77, vcc_lo, s72
	s_cselect_b32 s76, s47, s2
	s_cselect_b32 s79, s33, s73
	s_cselect_b32 s78, vcc_hi, s1
	s_cselect_b32 s75, s4, s75
	s_cselect_b32 s74, s97, s80
	s_cselect_b32 s73, s6, s55
	s_cselect_b32 s72, s5, s54
	s_waitcnt vmcnt(6)
	s_barrier
	v_mfma_f32_16x16x32_bf16 v[52:55], v[192:195], v[154:157], v[52:55]
	v_mfma_f32_16x16x32_bf16 v[48:51], v[200:203], v[154:157], v[48:51]
	v_mfma_f32_16x16x32_bf16 v[36:39], v[192:195], v[168:171], v[36:39]
	v_mfma_f32_16x16x32_bf16 v[32:35], v[200:203], v[168:171], v[32:35]
	v_mfma_f32_16x16x32_bf16 v[16:19], v[192:195], v[176:179], v[16:19]
	v_mfma_f32_16x16x32_bf16 v[8:11], v[200:203], v[176:179], v[8:11]
	v_mfma_f32_16x16x32_bf16 v[4:7], v[192:195], v[184:187], v[4:7]
	v_mfma_f32_16x16x32_bf16 v[0:3], v[200:203], v[184:187], v[0:3]
	v_mfma_f32_16x16x32_bf16 v[52:55], v[196:199], v[164:167], v[52:55]
	v_mfma_f32_16x16x32_bf16 v[48:51], v[204:207], v[164:167], v[48:51]
	v_mfma_f32_16x16x32_bf16 v[36:39], v[196:199], v[172:175], v[36:39]
	v_mfma_f32_16x16x32_bf16 v[32:35], v[204:207], v[172:175], v[32:35]
	v_mfma_f32_16x16x32_bf16 v[16:19], v[196:199], v[180:183], v[16:19]
	v_mfma_f32_16x16x32_bf16 v[8:11], v[204:207], v[180:183], v[8:11]
	v_mfma_f32_16x16x32_bf16 v[4:7], v[196:199], v[188:191], v[4:7]
	v_mfma_f32_16x16x32_bf16 v[0:3], v[204:207], v[188:191], v[0:3]
	s_cmp_gt_u32 s7, 29
	s_barrier
	s_cbranch_scc0 .LBB0_42
	s_lshl_b32 s0, s66, 8
	v_mov_b32_e32 v128, v161
	v_mov_b32_e32 v129, v160
	s_add_i32 s0, s0, s67
	s_and_b64 vcc, exec, s[18:19]
	v_add_u32_e32 v156, s0, v129
	s_lshl_b32 s0, s46, 8
	s_or_b32 s0, s0, s83
	v_lshl_add_u32 v128, v128, 3, s0
	v_ashrrev_i32_e32 v157, 31, v156
	v_ashrrev_i32_e32 v129, 31, v128
	v_lshlrev_b64 v[212:213], 13, v[156:157]
	v_lshl_add_u64 v[130:131], s[8:9], 0, v[212:213]
	v_lshlrev_b64 v[154:155], 2, v[128:129]
	v_lshl_add_u64 v[128:129], v[130:131], 0, v[154:155]
	global_load_dwordx4 v[164:167], v[128:129], off offset:16
	global_load_dwordx4 v[168:171], v[128:129], off
	global_load_dwordx4 v[172:175], v[128:129], off offset:528
	global_load_dwordx4 v[176:179], v[128:129], off offset:512
	v_add_u32_e32 v128, 16, v156
	v_ashrrev_i32_e32 v129, 31, v128
	v_lshlrev_b64 v[214:215], 13, v[128:129]
	v_lshl_add_u64 v[128:129], s[8:9], 0, v[214:215]
	v_lshl_add_u64 v[128:129], v[128:129], 0, v[154:155]
	global_load_dwordx4 v[180:183], v[128:129], off offset:16
	global_load_dwordx4 v[184:187], v[128:129], off
	global_load_dwordx4 v[188:191], v[128:129], off offset:528
	global_load_dwordx4 v[192:195], v[128:129], off offset:512
	v_add_u32_e32 v128, 32, v156
	v_ashrrev_i32_e32 v129, 31, v128
	v_lshlrev_b64 v[216:217], 13, v[128:129]
	v_lshl_add_u64 v[128:129], s[8:9], 0, v[216:217]
	v_lshl_add_u64 v[128:129], v[128:129], 0, v[154:155]
	global_load_dwordx4 v[196:199], v[128:129], off offset:16
	global_load_dwordx4 v[200:203], v[128:129], off
	global_load_dwordx4 v[204:207], v[128:129], off offset:528
	global_load_dwordx4 v[208:211], v[128:129], off offset:512
	v_add_u32_e32 v128, 48, v156
	v_ashrrev_i32_e32 v129, 31, v128
	v_lshlrev_b64 v[158:159], 13, v[128:129]
	v_lshl_add_u64 v[128:129], s[8:9], 0, v[158:159]
	v_lshl_add_u64 v[136:137], v[128:129], 0, v[154:155]
	global_load_dwordx4 v[132:135], v[136:137], off offset:16
	global_load_dwordx4 v[140:143], v[136:137], off
	global_load_dwordx4 v[128:131], v[136:137], off offset:528
	s_nop 0
	global_load_dwordx4 v[136:139], v[136:137], off offset:512
	v_lshl_add_u64 v[212:213], s[16:17], 0, v[212:213]
	s_mov_b32 s46, s22
	s_mov_b32 s66, s20
	s_mov_b64 s[68:69], s[64:65]
	s_mov_b64 s[70:71], s[62:63]
	s_movk_i32 s54, 0x4000
	s_movk_i32 s55, 0x6000
	v_readlane_b32 s0, v255, 23
	s_cmpk_gt_u32 s0, 0xff
	s_cbranch_scc1 .Lds_out_x
	s_barrier

; #define G_STAGE(bufoff, gbase, voff) do { _Pragma("unroll") for (int _i = 0; _i < 2; ++_i) \
;         __builtin_amdgcn_global_load_lds((const unsigned*)((const char*)(gbase) + (voff)[_i]), (LAS unsigned*)(lds + (bufoff) + ldsw + _i * 8192), 16, 0, 0); } while (0)
; #define G_LDA(dst, b, h) do { _Pragma("unroll") for (int m = 0; m < 4; ++m) _Pragma("unroll") for (int k = 0; k < 2; ++k) dst[m][k] = *(const LAS bf16x8*)(lds + G_SA(b, h) + aoff + m * 2048 + k * 1024); } while (0)
; #define G_LDB(dst, b, h) do { _Pragma("unroll") for (int n = 0; n < 2; ++n) _Pragma("unroll") for (int k = 0; k < 2; ++k) dst[n][k] = *(const LAS bf16x8*)(lds + G_SB(b, h) + boff + n * 2048 + k * 1024); } while (0)
; #define G_MMA(ai, bj, At, Bt) do { __builtin_amdgcn_s_setprio(1); _Pragma("unroll") for (int m = 0; m < 4; ++m) _Pragma("unroll") for (int n = 0; n < 2; ++n) _Pragma("unroll") for (int k = 0; k < 2; ++k) \
;         acc[ai][bj][m][n] = __builtin_amdgcn_mfma_f32_16x16x32_bf16(Bt[n][k], At[m][k], acc[ai][bj][m][n], 0, 0, 0); __builtin_amdgcn_s_setprio(0); } while (0)
; #define G_WAIT_V(n) asm volatile("s_waitcnt vmcnt(" #n ")" ::: "memory")
; #define G_WAIT_L(n) asm volatile("s_waitcnt lgkmcnt(" #n ")" ::: "memory")
; #define G_BAR __builtin_amdgcn_s_barrier()
; #define G_SCHED __builtin_amdgcn_sched_barrier(0)
; template <class J>
; DI void gemm_phase(LAS unsigned char* lds, const J& job) {
;     ...
;       G_LDB(B0, 0, 0); G_SCHED; G_LDA(At, 0, 0); G_STAGE(G_SA(1, 1), a1 + hstepA, voffA);
;       G_WAIT_L(8); G_BAR; G_WAIT_L(0); G_MMA(0, 0, At, B0); G_BAR; G_SCHED;
;       G_LDB(B1, 0, 1); G_STAGE(G_SB(0, 0), b2, voffB);
;       G_BAR; G_WAIT_L(0); G_MMA(0, 1, At, B1); G_BAR;
;       G_LDA(At, 0, 1); G_STAGE(G_SA(0, 0), a2, voffA);
;       G_BAR; G_WAIT_L(0); G_MMA(1, 0, At, B0); G_BAR; G_SCHED;
;       G_STAGE(G_SB(0, 1), b2 + hstepB, voffB);
;       G_WAIT_V(6); G_BAR; G_MMA(1, 1, At, B1); G_BAR;
.LBB0_74:
	s_add_i32 s2, s84, 0x100
	ds_read_b128 v[84:87], v204
	ds_read_b128 v[88:91], v204 offset:1024
	ds_read_b128 v[96:99], v204 offset:2048
	ds_read_b128 v[100:103], v204 offset:3072
	s_add_u32 s0, s19, s0
	s_addc_u32 s1, s21, 0
	s_add_i32 m0, s14, 0xc000
	ds_read_b128 v[154:157], v249
	ds_read_b128 v[158:161], v249 offset:1024
	ds_read_b128 v[162:165], v249 offset:2048
	ds_read_b128 v[166:169], v249 offset:3072
	ds_read_b128 v[170:173], v249 offset:4096
	ds_read_b128 v[174:177], v249 offset:5120
	ds_read_b128 v[178:181], v249 offset:6144
	ds_read_b128 v[182:185], v249 offset:7168
	global_load_lds_dwordx4 v148, s[0:1]
	s_add_i32 m0, s14, 0xe000
	s_nop 0
	global_load_lds_dwordx4 v150, s[0:1]
	s_waitcnt lgkmcnt(8)
	s_barrier
	s_waitcnt lgkmcnt(0)
	v_mfma_f32_16x16x32_bf16 v[140:143], v[84:87], v[154:157], v[140:143]
	v_mfma_f32_16x16x32_bf16 v[136:139], v[96:99], v[154:157], v[136:139]
	v_mfma_f32_16x16x32_bf16 v[124:127], v[84:87], v[162:165], v[124:127]
	v_mfma_f32_16x16x32_bf16 v[120:123], v[96:99], v[162:165], v[120:123]
	v_mfma_f32_16x16x32_bf16 v[108:111], v[84:87], v[170:173], v[108:111]
	v_mfma_f32_16x16x32_bf16 v[104:107], v[96:99], v[170:173], v[104:107]
	v_mfma_f32_16x16x32_bf16 v[76:79], v[84:87], v[178:181], v[76:79]
	v_mfma_f32_16x16x32_bf16 v[72:75], v[96:99], v[178:181], v[72:75]
	v_mfma_f32_16x16x32_bf16 v[140:143], v[88:91], v[158:161], v[140:143]
	v_mfma_f32_16x16x32_bf16 v[136:139], v[100:103], v[158:161], v[136:139]
	v_mfma_f32_16x16x32_bf16 v[124:127], v[88:91], v[166:169], v[124:127]
	v_mfma_f32_16x16x32_bf16 v[120:123], v[100:103], v[166:169], v[120:123]
	v_mfma_f32_16x16x32_bf16 v[108:111], v[88:91], v[174:177], v[108:111]
	v_mfma_f32_16x16x32_bf16 v[104:107], v[100:103], v[174:177], v[104:107]
	v_mfma_f32_16x16x32_bf16 v[76:79], v[88:91], v[182:185], v[76:79]
	v_mfma_f32_16x16x32_bf16 v[72:75], v[100:103], v[182:185], v[72:75]
	s_barrier
	s_add_i32 s38, s85, 0x100
	s_add_i32 s0, s2, s78
	s_mov_b32 m0, s0
	ds_read_b128 v[186:189], v204 offset:16384
	ds_read_b128 v[190:193], v204 offset:17408
	ds_read_b128 v[194:197], v204 offset:18432
	ds_read_b128 v[198:201], v204 offset:19456
	global_load_lds_dwordx4 v146, s[76:77]
	s_add_i32 m0, s0, 0x2000
	s_nop 0
	global_load_lds_dwordx4 v152, s[76:77]
	s_barrier
	s_waitcnt lgkmcnt(0)
	v_mfma_f32_16x16x32_bf16 v[132:135], v[186:189], v[154:157], v[132:135]
	v_mfma_f32_16x16x32_bf16 v[128:131], v[194:197], v[154:157], v[128:131]
	v_mfma_f32_16x16x32_bf16 v[116:119], v[186:189], v[162:165], v[116:119]
	v_mfma_f32_16x16x32_bf16 v[112:115], v[194:197], v[162:165], v[112:115]
	v_mfma_f32_16x16x32_bf16 v[92:95], v[186:189], v[170:173], v[92:95]
	v_mfma_f32_16x16x32_bf16 v[80:83], v[194:197], v[170:173], v[80:83]
	v_mfma_f32_16x16x32_bf16 v[68:71], v[186:189], v[178:181], v[68:71]
	v_mfma_f32_16x16x32_bf16 v[64:67], v[194:197], v[178:181], v[64:67]
	v_mfma_f32_16x16x32_bf16 v[132:135], v[190:193], v[158:161], v[132:135]
	v_mfma_f32_16x16x32_bf16 v[128:131], v[198:201], v[158:161], v[128:131]
	v_mfma_f32_16x16x32_bf16 v[116:119], v[190:193], v[166:169], v[116:119]
	v_mfma_f32_16x16x32_bf16 v[112:115], v[198:201], v[166:169], v[112:115]
	v_mfma_f32_16x16x32_bf16 v[92:95], v[190:193], v[174:177], v[92:95]
	v_mfma_f32_16x16x32_bf16 v[80:83], v[198:201], v[174:177], v[80:83]
	v_mfma_f32_16x16x32_bf16 v[68:71], v[190:193], v[182:185], v[68:71]
	v_mfma_f32_16x16x32_bf16 v[64:67], v[198:201], v[182:185], v[64:67]
	s_mov_b32 m0, s14
	s_barrier
	ds_read_b128 v[154:157], v249 offset:16384
	ds_read_b128 v[158:161], v249 offset:17408
	ds_read_b128 v[162:165], v249 offset:18432
	ds_read_b128 v[166:169], v249 offset:19456
	ds_read_b128 v[170:173], v249 offset:20480
	ds_read_b128 v[174:177], v249 offset:21504
	ds_read_b128 v[178:181], v249 offset:22528
	ds_read_b128 v[182:185], v249 offset:23552
	global_load_lds_dwordx4 v148, s[74:75]
	s_mov_b32 m0, s15
	s_nop 0
	global_load_lds_dwordx4 v150, s[74:75]
	s_barrier
	s_waitcnt lgkmcnt(0)
	v_mfma_f32_16x16x32_bf16 v[60:63], v[84:87], v[154:157], v[60:63]
	v_mfma_f32_16x16x32_bf16 v[56:59], v[96:99], v[154:157], v[56:59]
	v_mfma_f32_16x16x32_bf16 v[44:47], v[84:87], v[162:165], v[44:47]
	v_mfma_f32_16x16x32_bf16 v[40:43], v[96:99], v[162:165], v[40:43]
	v_mfma_f32_16x16x32_bf16 v[28:31], v[84:87], v[170:173], v[28:31]
	v_mfma_f32_16x16x32_bf16 v[24:27], v[96:99], v[170:173], v[24:27]
	v_mfma_f32_16x16x32_bf16 v[12:15], v[84:87], v[178:181], v[12:15]
	v_mfma_f32_16x16x32_bf16 v[8:11], v[96:99], v[178:181], v[8:11]
	v_mfma_f32_16x16x32_bf16 v[60:63], v[88:91], v[158:161], v[60:63]
	v_mfma_f32_16x16x32_bf16 v[56:59], v[100:103], v[158:161], v[56:59]
	v_mfma_f32_16x16x32_bf16 v[44:47], v[88:91], v[166:169], v[44:47]
	v_mfma_f32_16x16x32_bf16 v[40:43], v[100:103], v[166:169], v[40:43]
	v_mfma_f32_16x16x32_bf16 v[28:31], v[88:91], v[174:177], v[28:31]
	v_mfma_f32_16x16x32_bf16 v[24:27], v[100:103], v[174:177], v[24:27]
	v_mfma_f32_16x16x32_bf16 v[12:15], v[88:91], v[182:185], v[12:15]
	v_mfma_f32_16x16x32_bf16 v[8:11], v[100:103], v[182:185], v[8:11]
	s_barrier
	s_add_u32 s0, s76, 0x1000000
	s_addc_u32 s1, s77, 0
	s_add_i32 s2, s38, s78
	s_mov_b32 m0, s2
	s_nop 0
	global_load_lds_dwordx4 v146, s[0:1]
	s_add_i32 m0, s2, 0x2000
	s_nop 0
	global_load_lds_dwordx4 v152, s[0:1]
	s_waitcnt vmcnt(6)
	s_barrier
; #define G_STAGE(bufoff, gbase, voff) do { _Pragma("unroll") for (int _i = 0; _i < 2; ++_i) \
;         __builtin_amdgcn_global_load_lds((const unsigned*)((const char*)(gbase) + (voff)[_i]), (LAS unsigned*)(lds + (bufoff) + ldsw + _i * 8192), 16, 0, 0); } while (0)
; #define G_LDA(dst, b, h) do { _Pragma("unroll") for (int m = 0; m < 4; ++m) _Pragma("unroll") for (int k = 0; k < 2; ++k) dst[m][k] = *(const LAS bf16x8*)(lds + G_SA(b, h) + aoff + m * 2048 + k * 1024); } while (0)
; #define G_LDB(dst, b, h) do { _Pragma("unroll") for (int n = 0; n < 2; ++n) _Pragma("unroll") for (int k = 0; k < 2; ++k) dst[n][k] = *(const LAS bf16x8*)(lds + G_SB(b, h) + boff + n * 2048 + k * 1024); } while (0)
; #define G_MMA(ai, bj, At, Bt) do { __builtin_amdgcn_s_setprio(1); _Pragma("unroll") for (int m = 0; m < 4; ++m) _Pragma("unroll") for (int n = 0; n < 2; ++n) _Pragma("unroll") for (int k = 0; k < 2; ++k) \
;         acc[ai][bj][m][n] = __builtin_amdgcn_mfma_f32_16x16x32_bf16(Bt[n][k], At[m][k], acc[ai][bj][m][n], 0, 0, 0); __builtin_amdgcn_s_setprio(0); } while (0)
; #define G_WAIT_V(n) asm volatile("s_waitcnt vmcnt(" #n ")" ::: "memory")
; #define G_WAIT_L(n) asm volatile("s_waitcnt lgkmcnt(" #n ")" ::: "memory")
; #define G_BAR __builtin_amdgcn_s_barrier()
; #define G_SCHED __builtin_amdgcn_sched_barrier(0)
; template <class J>
; DI void gemm_phase(LAS unsigned char* lds, const J& job) {
;     ...
;       G_WAIT_V(6); G_BAR; G_MMA(1, 1, At, B1); G_BAR;
;       G_LDB(B0, 1, 0); G_SCHED; G_LDA(At, 1, 0); G_STAGE(G_SA(0, 1), a2 + hstepA, voffA);
;       G_WAIT_L(8); G_BAR; G_WAIT_L(0); G_MMA(0, 0, At, B0); G_BAR; G_SCHED;
;       G_LDB(B1, 1, 1); G_STAGE(G_SB(1, 0), b3, voffB);
;       G_BAR; G_WAIT_L(0); G_MMA(0, 1, At, B1); G_BAR;
;       G_LDA(At, 1, 1); G_STAGE(G_SA(1, 0), a3, voffA);
;       G_BAR; G_WAIT_L(0); G_MMA(1, 0, At, B0); G_BAR; G_SCHED;
	v_mfma_f32_16x16x32_bf16 v[52:55], v[186:189], v[154:157], v[52:55]
	v_mfma_f32_16x16x32_bf16 v[48:51], v[194:197], v[154:157], v[48:51]
	v_mfma_f32_16x16x32_bf16 v[36:39], v[186:189], v[162:165], v[36:39]
	v_mfma_f32_16x16x32_bf16 v[32:35], v[194:197], v[162:165], v[32:35]
	v_mfma_f32_16x16x32_bf16 v[20:23], v[186:189], v[170:173], v[20:23]
	v_mfma_f32_16x16x32_bf16 v[16:19], v[194:197], v[170:173], v[16:19]
	v_mfma_f32_16x16x32_bf16 v[4:7], v[186:189], v[178:181], v[4:7]
	v_mfma_f32_16x16x32_bf16 v[0:3], v[194:197], v[178:181], v[0:3]
	v_mfma_f32_16x16x32_bf16 v[52:55], v[190:193], v[158:161], v[52:55]
	v_mfma_f32_16x16x32_bf16 v[48:51], v[198:201], v[158:161], v[48:51]
	v_mfma_f32_16x16x32_bf16 v[36:39], v[190:193], v[166:169], v[36:39]
	v_mfma_f32_16x16x32_bf16 v[32:35], v[198:201], v[166:169], v[32:35]
	v_mfma_f32_16x16x32_bf16 v[20:23], v[190:193], v[174:177], v[20:23]
	v_mfma_f32_16x16x32_bf16 v[16:19], v[198:201], v[174:177], v[16:19]
	v_mfma_f32_16x16x32_bf16 v[4:7], v[190:193], v[182:185], v[4:7]
	v_mfma_f32_16x16x32_bf16 v[0:3], v[198:201], v[182:185], v[0:3]
	s_add_i32 s2, s88, 0x100
	s_barrier
	ds_read_b128 v[84:87], v204 offset:32768
	ds_read_b128 v[88:91], v204 offset:33792
	ds_read_b128 v[96:99], v204 offset:34816
	ds_read_b128 v[100:103], v204 offset:35840
	s_add_u32 s0, s74, 0x80000
	s_addc_u32 s1, s75, 0
	s_mov_b32 m0, s83
	ds_read_b128 v[154:157], v249 offset:32768
	ds_read_b128 v[158:161], v249 offset:33792
	ds_read_b128 v[162:165], v249 offset:34816
	ds_read_b128 v[166:169], v249 offset:35840
	ds_read_b128 v[170:173], v249 offset:36864
	ds_read_b128 v[174:177], v249 offset:37888
	ds_read_b128 v[178:181], v249 offset:38912
	ds_read_b128 v[182:185], v249 offset:39936
	global_load_lds_dwordx4 v148, s[0:1]
	s_mov_b32 m0, s36
	s_nop 0
	global_load_lds_dwordx4 v150, s[0:1]
	s_waitcnt lgkmcnt(8)
	s_barrier
	s_waitcnt lgkmcnt(0)
	v_mfma_f32_16x16x32_bf16 v[140:143], v[84:87], v[154:157], v[140:143]
	v_mfma_f32_16x16x32_bf16 v[136:139], v[96:99], v[154:157], v[136:139]
	v_mfma_f32_16x16x32_bf16 v[124:127], v[84:87], v[162:165], v[124:127]
	v_mfma_f32_16x16x32_bf16 v[120:123], v[96:99], v[162:165], v[120:123]
	v_mfma_f32_16x16x32_bf16 v[108:111], v[84:87], v[170:173], v[108:111]
	v_mfma_f32_16x16x32_bf16 v[104:107], v[96:99], v[170:173], v[104:107]
	v_mfma_f32_16x16x32_bf16 v[76:79], v[84:87], v[178:181], v[76:79]
	v_mfma_f32_16x16x32_bf16 v[72:75], v[96:99], v[178:181], v[72:75]
	v_mfma_f32_16x16x32_bf16 v[140:143], v[88:91], v[158:161], v[140:143]
	v_mfma_f32_16x16x32_bf16 v[136:139], v[100:103], v[158:161], v[136:139]
	v_mfma_f32_16x16x32_bf16 v[124:127], v[88:91], v[166:169], v[124:127]
	v_mfma_f32_16x16x32_bf16 v[120:123], v[100:103], v[166:169], v[120:123]
	v_mfma_f32_16x16x32_bf16 v[108:111], v[88:91], v[174:177], v[108:111]
	v_mfma_f32_16x16x32_bf16 v[104:107], v[100:103], v[174:177], v[104:107]
	v_mfma_f32_16x16x32_bf16 v[76:79], v[88:91], v[182:185], v[76:79]
	v_mfma_f32_16x16x32_bf16 v[72:75], v[100:103], v[182:185], v[72:75]
	s_barrier
	s_add_i32 s38, s89, 0x100
	s_add_i32 s0, s2, s78
	s_mov_b32 m0, s0
	ds_read_b128 v[186:189], v204 offset:49152
	ds_read_b128 v[190:193], v204 offset:50176
	ds_read_b128 v[194:197], v204 offset:51200
	ds_read_b128 v[198:201], v204 offset:52224
	global_load_lds_dwordx4 v146, s[70:71]
	s_add_i32 m0, s0, 0x2000
	s_nop 0
	global_load_lds_dwordx4 v152, s[70:71]
	s_barrier
	s_waitcnt lgkmcnt(0)
	v_mfma_f32_16x16x32_bf16 v[132:135], v[186:189], v[154:157], v[132:135]
	v_mfma_f32_16x16x32_bf16 v[128:131], v[194:197], v[154:157], v[128:131]
	v_mfma_f32_16x16x32_bf16 v[116:119], v[186:189], v[162:165], v[116:119]
	v_mfma_f32_16x16x32_bf16 v[112:115], v[194:197], v[162:165], v[112:115]
	v_mfma_f32_16x16x32_bf16 v[92:95], v[186:189], v[170:173], v[92:95]
	v_mfma_f32_16x16x32_bf16 v[80:83], v[194:197], v[170:173], v[80:83]
	v_mfma_f32_16x16x32_bf16 v[68:71], v[186:189], v[178:181], v[68:71]
	v_mfma_f32_16x16x32_bf16 v[64:67], v[194:197], v[178:181], v[64:67]
	v_mfma_f32_16x16x32_bf16 v[132:135], v[190:193], v[158:161], v[132:135]
	v_mfma_f32_16x16x32_bf16 v[128:131], v[198:201], v[158:161], v[128:131]
	v_mfma_f32_16x16x32_bf16 v[116:119], v[190:193], v[166:169], v[116:119]
	v_mfma_f32_16x16x32_bf16 v[112:115], v[198:201], v[166:169], v[112:115]
	v_mfma_f32_16x16x32_bf16 v[92:95], v[190:193], v[174:177], v[92:95]
	v_mfma_f32_16x16x32_bf16 v[80:83], v[198:201], v[174:177], v[80:83]
	v_mfma_f32_16x16x32_bf16 v[68:71], v[190:193], v[182:185], v[68:71]
	v_mfma_f32_16x16x32_bf16 v[64:67], v[198:201], v[182:185], v[64:67]
	s_mov_b32 m0, s24
	s_barrier
	ds_read_b128 v[154:157], v249 offset:49152
	ds_read_b128 v[158:161], v249 offset:50176
	ds_read_b128 v[162:165], v249 offset:51200
	ds_read_b128 v[166:169], v249 offset:52224
	ds_read_b128 v[170:173], v249 offset:53248
	ds_read_b128 v[174:177], v249 offset:54272
	ds_read_b128 v[178:181], v249 offset:55296
	ds_read_b128 v[182:185], v249 offset:56320
	global_load_lds_dwordx4 v148, s[72:73]
	s_mov_b32 m0, s25
	s_nop 0
	global_load_lds_dwordx4 v150, s[72:73]
	s_barrier
	s_waitcnt lgkmcnt(0)
	v_mfma_f32_16x16x32_bf16 v[60:63], v[84:87], v[154:157], v[60:63]
	v_mfma_f32_16x16x32_bf16 v[56:59], v[96:99], v[154:157], v[56:59]
	v_mfma_f32_16x16x32_bf16 v[44:47], v[84:87], v[162:165], v[44:47]
	v_mfma_f32_16x16x32_bf16 v[40:43], v[96:99], v[162:165], v[40:43]
	v_mfma_f32_16x16x32_bf16 v[28:31], v[84:87], v[170:173], v[28:31]
	v_mfma_f32_16x16x32_bf16 v[24:27], v[96:99], v[170:173], v[24:27]
	v_mfma_f32_16x16x32_bf16 v[12:15], v[84:87], v[178:181], v[12:15]
	v_mfma_f32_16x16x32_bf16 v[8:11], v[96:99], v[178:181], v[8:11]
	v_mfma_f32_16x16x32_bf16 v[60:63], v[88:91], v[158:161], v[60:63]
	v_mfma_f32_16x16x32_bf16 v[56:59], v[100:103], v[158:161], v[56:59]
	v_mfma_f32_16x16x32_bf16 v[44:47], v[88:91], v[166:169], v[44:47]
	v_mfma_f32_16x16x32_bf16 v[40:43], v[100:103], v[166:169], v[40:43]
	v_mfma_f32_16x16x32_bf16 v[28:31], v[88:91], v[174:177], v[28:31]
	v_mfma_f32_16x16x32_bf16 v[24:27], v[100:103], v[174:177], v[24:27]
	v_mfma_f32_16x16x32_bf16 v[12:15], v[88:91], v[182:185], v[12:15]
	v_mfma_f32_16x16x32_bf16 v[8:11], v[100:103], v[182:185], v[8:11]
	s_barrier
; #define G_STAGE(bufoff, gbase, voff) do { _Pragma("unroll") for (int _i = 0; _i < 2; ++_i) \
;         __builtin_amdgcn_global_load_lds((const unsigned*)((const char*)(gbase) + (voff)[_i]), (LAS unsigned*)(lds + (bufoff) + ldsw + _i * 8192), 16, 0, 0); } while (0)
; #define G_LDA(dst, b, h) do { _Pragma("unroll") for (int m = 0; m < 4; ++m) _Pragma("unroll") for (int k = 0; k < 2; ++k) dst[m][k] = *(const LAS bf16x8*)(lds + G_SA(b, h) + aoff + m * 2048 + k * 1024); } while (0)
; #define G_LDB(dst, b, h) do { _Pragma("unroll") for (int n = 0; n < 2; ++n) _Pragma("unroll") for (int k = 0; k < 2; ++k) dst[n][k] = *(const LAS bf16x8*)(lds + G_SB(b, h) + boff + n * 2048 + k * 1024); } while (0)
; #define G_WAIT_V(n) asm volatile("s_waitcnt vmcnt(" #n ")" ::: "memory")
; #define G_WAIT_L(n) asm volatile("s_waitcnt lgkmcnt(" #n ")" ::: "memory")
; #define G_BAR __builtin_amdgcn_s_barrier()
; #define G_SCHED __builtin_amdgcn_sched_barrier(0)
; template <class J>
; DI void gemm_phase(LAS unsigned char* lds, const J& job) {
;     ...
;       const bool last = (t == nt - 2);
;       const char* a1 = cA + G_KT(t + 1);
;       const char* a2 = last ? nA + G_KT(0) : cA + G_KT(t + 2); const char* b2 = last ? nB + G_KT(0) : cB + G_KT(t + 2);
;       const char* a3 = last ? nA + G_KT(1) : cA + G_KT(t + 3); const char* b3 = last ? nB + G_KT(1) : cB + G_KT(t + 3);
;       G_LDB(B0, 0, 0); G_SCHED; G_LDA(At, 0, 0); G_STAGE(G_SA(1, 1), a1 + hstepA, voffA);
;       G_WAIT_L(8); G_BAR; G_WAIT_L(0); G_MMA(0, 0, At, B0); G_BAR; G_SCHED;
;       G_LDB(B1, 0, 1); G_STAGE(G_SB(0, 0), b2, voffB);
;       G_BAR; G_WAIT_L(0); G_MMA(0, 1, At, B1); G_BAR;
;       G_LDA(At, 0, 1); G_STAGE(G_SA(0, 0), a2, voffA);
;       G_BAR; G_WAIT_L(0); G_MMA(1, 0, At, B0); G_BAR; G_SCHED;
;       G_STAGE(G_SB(0, 1), b2 + hstepB, voffB);
;       G_WAIT_V(6); G_BAR; G_MMA(1, 1, At, B1); G_BAR;
;       G_LDB(B0, 1, 0); G_SCHED; G_LDA(At, 1, 0); G_STAGE(G_SA(0, 1), a2 + hstepA, voffA);
;       G_WAIT_L(8); G_BAR; G_WAIT_L(0); G_MMA(0, 0, At, B0); G_BAR; G_SCHED;
;       G_LDB(B1, 1, 1); G_STAGE(G_SB(1, 0), b3, voffB);
;       G_BAR; G_WAIT_L(0); G_MMA(0, 1, At, B1); G_BAR;
;       G_LDA(At, 1, 1); G_STAGE(G_SA(1, 0), a3, voffA);
;       G_BAR; G_WAIT_L(0); G_MMA(1, 0, At, B0); G_BAR; G_SCHED;
;       G_STAGE(G_SB(1, 1), b3 + hstepB, voffB);
;       G_WAIT_V(6); G_BAR; G_MMA(1, 1, At, B1); G_BAR;
	s_add_u32 s0, s70, 0x1000000
	s_addc_u32 s1, s71, 0
	s_add_i32 s2, s38, s78
	s_mov_b32 m0, s2
	s_nop 0
	global_load_lds_dwordx4 v146, s[0:1]
	s_add_i32 m0, s2, 0x2000
	s_nop 0
	global_load_lds_dwordx4 v152, s[0:1]
	s_add_i32 s6, s6, 2
	s_addk_i32 s56, 0x100
	s_addk_i32 s7, 0x100
	s_add_i32 s1, s56, 0xffffff80
	s_and_b32 s0, s7, 0xf80
	s_and_b32 s1, s1, 0xf00
	s_add_u32 s57, s68, s1
	s_addc_u32 s70, s69, 0
	s_add_u32 s1, s66, s1
	s_addc_u32 s71, s67, 0
	s_and_b32 s72, s56, 0xf80
	s_add_u32 s80, s68, s72
	s_addc_u32 s73, s69, 0
	s_add_u32 s38, s66, s72
	s_addc_u32 s2, s67, 0
	s_cmp_eq_u32 s6, 28
	s_cselect_b32 s75, s46, s70
	s_cselect_b32 s74, s45, s57
	s_cselect_b32 s77, vcc_lo, s71
	s_cselect_b32 s76, s47, s1
	s_cselect_b32 s73, s97, s73
	s_cselect_b32 s72, s33, s80
	s_cselect_b32 s71, s5, s2
	s_cselect_b32 s70, vcc_hi, s38
	s_waitcnt vmcnt(6)
	s_barrier
	v_mfma_f32_16x16x32_bf16 v[52:55], v[186:189], v[154:157], v[52:55]
	v_mfma_f32_16x16x32_bf16 v[48:51], v[194:197], v[154:157], v[48:51]
	v_mfma_f32_16x16x32_bf16 v[36:39], v[186:189], v[162:165], v[36:39]
	v_mfma_f32_16x16x32_bf16 v[32:35], v[194:197], v[162:165], v[32:35]
	v_mfma_f32_16x16x32_bf16 v[20:23], v[186:189], v[170:173], v[20:23]
	v_mfma_f32_16x16x32_bf16 v[16:19], v[194:197], v[170:173], v[16:19]
	v_mfma_f32_16x16x32_bf16 v[4:7], v[186:189], v[178:181], v[4:7]
	v_mfma_f32_16x16x32_bf16 v[0:3], v[194:197], v[178:181], v[0:3]
	v_mfma_f32_16x16x32_bf16 v[52:55], v[190:193], v[158:161], v[52:55]
	v_mfma_f32_16x16x32_bf16 v[48:51], v[198:201], v[158:161], v[48:51]
	v_mfma_f32_16x16x32_bf16 v[36:39], v[190:193], v[166:169], v[36:39]
	v_mfma_f32_16x16x32_bf16 v[32:35], v[198:201], v[166:169], v[32:35]
	v_mfma_f32_16x16x32_bf16 v[20:23], v[190:193], v[174:177], v[20:23]
	v_mfma_f32_16x16x32_bf16 v[16:19], v[198:201], v[174:177], v[16:19]
	v_mfma_f32_16x16x32_bf16 v[4:7], v[190:193], v[182:185], v[4:7]
	v_mfma_f32_16x16x32_bf16 v[0:3], v[198:201], v[182:185], v[0:3]
	s_cmp_gt_u32 s6, 29
	s_barrier
	s_cbranch_scc0 .LBB0_74
;   DI void epi(const Acc& acc, const Unit& u, int wr, int wc, int fr, int fq) const {
;     const int cc = u.pn * 64 + 16 * wc + 4 * fq;
;     u32x2 zz[2][4][4];
; #pragma unroll
;     for (int ai = 0; ai < 2; ++ai)
; #pragma unroll
;       for (int m = 0; m < 4; ++m) {
;         const u16* zr = Z + (size_t)(u.pm * 256 + ai * HALF + wr * 64 + m * 16 + fr) * NGATE + cc;
; #pragma unroll
;         for (int br = 0; br < 4; ++br) zz[ai][m][br] = *(const u32x2*)(zr + br * 2048);
;       }
;     f32x4 bg[4];
; #pragma unroll
;     for (int br = 0; br < 4; ++br) bg[br] = *(const f32x4*)(bgate + br * 2048 + cc);
;     asm volatile("" ::: "memory");
	v_mov_b32_e32 v84, v247
	v_mov_b32_e32 v85, v246
	s_lshl_b32 s0, s44, 6
	s_or_b32 s0, s0, s96
	v_lshl_add_u32 v84, v84, 2, s0
	s_lshl_b32 s0, s64, 8
	s_add_i32 s0, s0, s37
	v_add_u32_e32 v224, s0, v85
	v_ashrrev_i32_e32 v85, 31, v84
	v_lshlrev_b64 v[154:155], 1, v[84:85]
	v_ashrrev_i32_e32 v225, 31, v224
	v_lshl_add_u64 v[86:87], s[26:27], 0, v[154:155]
	v_lshlrev_b64 v[88:89], 14, v[224:225]
	v_lshl_add_u64 v[88:89], v[86:87], 0, v[88:89]
	v_add_co_u32_e32 v90, vcc, s82, v88
	v_add_u32_e32 v212, 16, v224
	s_nop 0
	v_addc_co_u32_e32 v91, vcc, 0, v89, vcc
	v_ashrrev_i32_e32 v213, 31, v212
	v_add_co_u32_e32 v96, vcc, s92, v88
	v_lshlrev_b64 v[98:99], 14, v[212:213]
	s_nop 0
	v_addc_co_u32_e32 v97, vcc, 0, v89, vcc
	v_lshl_add_u64 v[98:99], v[86:87], 0, v[98:99]
	v_add_co_u32_e32 v100, vcc, s82, v98
	v_add_u32_e32 v202, 32, v224
	s_nop 0
	v_addc_co_u32_e32 v101, vcc, 0, v99, vcc
	global_load_dwordx2 v[230:231], v[90:91], off offset:-4096
	global_load_dwordx2 v[226:227], v[90:91], off
	global_load_dwordx2 v[220:221], v[100:101], off offset:-4096
	global_load_dwordx2 v[214:215], v[100:101], off
	v_add_co_u32_e32 v90, vcc, s92, v98
	v_ashrrev_i32_e32 v203, 31, v202
	s_nop 0
	v_addc_co_u32_e32 v91, vcc, 0, v99, vcc
	global_load_dwordx2 v[232:233], v[88:89], off
	global_load_dwordx2 v[228:229], v[96:97], off
	global_load_dwordx2 v[222:223], v[98:99], off
	global_load_dwordx2 v[216:217], v[90:91], off
	v_lshlrev_b64 v[88:89], 14, v[202:203]
	v_lshl_add_u64 v[88:89], v[86:87], 0, v[88:89]
	v_add_co_u32_e32 v90, vcc, s82, v88
	v_add_u32_e32 v190, 48, v224
	s_nop 0
	v_addc_co_u32_e32 v91, vcc, 0, v89, vcc
	v_ashrrev_i32_e32 v191, 31, v190
	v_add_co_u32_e32 v96, vcc, s92, v88
	v_lshlrev_b64 v[98:99], 14, v[190:191]
	s_nop 0
	v_addc_co_u32_e32 v97, vcc, 0, v89, vcc
	v_lshl_add_u64 v[98:99], v[86:87], 0, v[98:99]
	v_add_co_u32_e32 v100, vcc, s82, v98
	v_add_u32_e32 v184, 0x80, v224
	s_nop 0
	v_addc_co_u32_e32 v101, vcc, 0, v99, vcc
	global_load_dwordx2 v[210:211], v[90:91], off offset:-4096
	global_load_dwordx2 v[206:207], v[90:91], off
	global_load_dwordx2 v[200:201], v[100:101], off offset:-4096
	global_load_dwordx2 v[192:193], v[100:101], off
	v_add_co_u32_e32 v90, vcc, s92, v98
	v_lshl_add_u64 v[84:85], v[84:85], 2, s[12:13]
	v_ashrrev_i32_e32 v185, 31, v184
	v_addc_co_u32_e32 v91, vcc, 0, v99, vcc
	global_load_dwordx4 v[100:103], v[84:85], off
	global_load_dwordx2 v[218:219], v[88:89], off
	global_load_dwordx2 v[208:209], v[96:97], off
	global_load_dwordx2 v[204:205], v[98:99], off
	global_load_dwordx2 v[198:199], v[90:91], off
	v_lshlrev_b64 v[88:89], 14, v[184:185]
	v_lshl_add_u64 v[88:89], v[86:87], 0, v[88:89]
	v_add_co_u32_e32 v90, vcc, s82, v88
	v_add_u32_e32 v174, 0x90, v224
	s_nop 0
	v_addc_co_u32_e32 v91, vcc, 0, v89, vcc
	v_add_co_u32_e32 v156, vcc, s92, v88
	v_ashrrev_i32_e32 v175, 31, v174
	s_nop 0
	v_addc_co_u32_e32 v157, vcc, 0, v89, vcc
	v_add_co_u32_e32 v96, vcc, s82, v84
	v_lshlrev_b64 v[158:159], 14, v[174:175]
	s_nop 0
	v_addc_co_u32_e32 v97, vcc, 0, v85, vcc
	global_load_dwordx4 v[96:99], v[96:97], off
	v_lshl_add_u64 v[158:159], v[86:87], 0, v[158:159]
	v_add_co_u32_e32 v160, vcc, s82, v158
	v_add_u32_e32 v164, 0xa0, v224
	s_nop 0
	v_addc_co_u32_e32 v161, vcc, 0, v159, vcc
	global_load_dwordx2 v[194:195], v[90:91], off offset:-4096
	global_load_dwordx2 v[186:187], v[90:91], off
	global_load_dwordx2 v[180:181], v[160:161], off offset:-4096
	global_load_dwordx2 v[176:177], v[160:161], off
	v_add_co_u32_e32 v90, vcc, s92, v158
	v_ashrrev_i32_e32 v165, 31, v164
	s_nop 0
	v_addc_co_u32_e32 v91, vcc, 0, v159, vcc
	global_load_dwordx2 v[196:197], v[88:89], off
	global_load_dwordx2 v[188:189], v[156:157], off
	global_load_dwordx2 v[182:183], v[158:159], off
	global_load_dwordx2 v[178:179], v[90:91], off
	v_lshlrev_b64 v[88:89], 14, v[164:165]
	v_lshl_add_u64 v[162:163], v[86:87], 0, v[88:89]
	v_add_co_u32_e32 v158, vcc, s82, v162
	v_add_u32_e32 v156, 0xb0, v224
	s_nop 0
	v_addc_co_u32_e32 v159, vcc, 0, v163, vcc
	v_add_co_u32_e32 v168, vcc, s92, v162
	v_ashrrev_i32_e32 v157, 31, v156
	s_nop 0
	v_addc_co_u32_e32 v169, vcc, 0, v163, vcc
	v_add_co_u32_e32 v88, vcc, s54, v84
	v_lshlrev_b64 v[160:161], 14, v[156:157]
	s_nop 0
	v_addc_co_u32_e32 v89, vcc, 0, v85, vcc
	global_load_dwordx4 v[88:91], v[88:89], off
	v_lshl_add_u64 v[250:251], v[86:87], 0, v[160:161]
	v_add_co_u32_e32 v86, vcc, s82, v250
	s_mov_b32 s44, s20
	s_nop 0
	v_addc_co_u32_e32 v87, vcc, 0, v251, vcc
	v_add_co_u32_e32 v84, vcc, s55, v84
	global_load_dwordx2 v[170:171], v[158:159], off offset:-4096
	global_load_dwordx2 v[166:167], v[158:159], off
	global_load_dwordx2 v[160:161], v[86:87], off offset:-4096
	s_nop 0
	global_load_dwordx2 v[158:159], v[86:87], off
	v_addc_co_u32_e32 v85, vcc, 0, v85, vcc
	global_load_dwordx4 v[84:87], v[84:85], off
	v_add_co_u32_e32 v252, vcc, s92, v250
	s_mov_b32 s64, s18
	s_nop 0
	v_addc_co_u32_e32 v253, vcc, 0, v251, vcc
	s_and_b64 vcc, exec, s[8:9]
	s_mov_b64 s[66:67], s[62:63]
	s_mov_b64 s[68:69], s[22:23]
	v_readlane_b32 s0, v255, 23
	s_cmpk_gt_u32 s0, 0xff
	s_cbranch_scc1 .Lds_gate_x
	s_barrier

; #define G_STAGE(bufoff, gbase, voff) do { _Pragma("unroll") for (int _i = 0; _i < 2; ++_i) \
;         __builtin_amdgcn_global_load_lds((const unsigned*)((const char*)(gbase) + (voff)[_i]), (LAS unsigned*)(lds + (bufoff) + ldsw + _i * 8192), 16, 0, 0); } while (0)
; #define G_LDA(dst, b, h) do { _Pragma("unroll") for (int m = 0; m < 4; ++m) _Pragma("unroll") for (int k = 0; k < 2; ++k) dst[m][k] = *(const LAS bf16x8*)(lds + G_SA(b, h) + aoff + m * 2048 + k * 1024); } while (0)
; #define G_LDB(dst, b, h) do { _Pragma("unroll") for (int n = 0; n < 2; ++n) _Pragma("unroll") for (int k = 0; k < 2; ++k) dst[n][k] = *(const LAS bf16x8*)(lds + G_SB(b, h) + boff + n * 2048 + k * 1024); } while (0)
; #define G_MMA(ai, bj, At, Bt) do { __builtin_amdgcn_s_setprio(1); _Pragma("unroll") for (int m = 0; m < 4; ++m) _Pragma("unroll") for (int n = 0; n < 2; ++n) _Pragma("unroll") for (int k = 0; k < 2; ++k) \
;         acc[ai][bj][m][n] = __builtin_amdgcn_mfma_f32_16x16x32_bf16(Bt[n][k], At[m][k], acc[ai][bj][m][n], 0, 0, 0); __builtin_amdgcn_s_setprio(0); } while (0)
; #define G_WAIT_V(n) asm volatile("s_waitcnt vmcnt(" #n ")" ::: "memory")
; #define G_WAIT_L(n) asm volatile("s_waitcnt lgkmcnt(" #n ")" ::: "memory")
; #define G_BAR __builtin_amdgcn_s_barrier()
; #define G_SCHED __builtin_amdgcn_sched_barrier(0)
; template <class J>
; DI void gemm_phase(LAS unsigned char* lds, const J& job) {
;     ...
;       G_LDB(B0, 0, 0); G_SCHED; G_LDA(At, 0, 0); G_STAGE(G_SA(1, 1), a1 + hstepA, voffA);
;       G_WAIT_L(8); G_BAR; G_WAIT_L(0); G_MMA(0, 0, At, B0); G_BAR; G_SCHED;
;       G_LDB(B1, 0, 1); G_STAGE(G_SB(0, 0), b2, voffB);
;       G_BAR; G_WAIT_L(0); G_MMA(0, 1, At, B1); G_BAR;
;       G_LDA(At, 0, 1); G_STAGE(G_SA(0, 0), a2, voffA);
;       G_BAR; G_WAIT_L(0); G_MMA(1, 0, At, B0); G_BAR; G_SCHED;
;       G_STAGE(G_SB(0, 1), b2 + hstepB, voffB);
;       G_WAIT_V(6); G_BAR; G_MMA(1, 1, At, B1); G_BAR;
.LBB0_104:
	s_add_i32 s1, s84, 0x100
	ds_read_b128 v[140:143], v208
	ds_read_b128 v[148:151], v208 offset:1024
	ds_read_b128 v[152:155], v208 offset:2048
	ds_read_b128 v[156:159], v208 offset:3072
	s_add_u32 vcc_lo, s9, s0
	s_addc_u32 vcc_hi, s17, 0
	s_add_i32 m0, s25, 0xc000
	ds_read_b128 v[160:163], v139
	ds_read_b128 v[164:167], v139 offset:1024
	ds_read_b128 v[168:171], v139 offset:2048
	ds_read_b128 v[172:175], v139 offset:3072
	ds_read_b128 v[176:179], v139 offset:4096
	ds_read_b128 v[180:183], v139 offset:5120
	ds_read_b128 v[184:187], v139 offset:6144
	ds_read_b128 v[188:191], v139 offset:7168
	global_load_lds_dwordx4 v132, vcc
	s_add_i32 m0, s25, 0xe000
	s_nop 0
	global_load_lds_dwordx4 v130, vcc
	s_waitcnt lgkmcnt(8)
	s_barrier
	s_waitcnt lgkmcnt(0)
	v_mfma_f32_16x16x32_bf16 v[124:127], v[140:143], v[160:163], v[124:127]
	v_mfma_f32_16x16x32_bf16 v[120:123], v[152:155], v[160:163], v[120:123]
	v_mfma_f32_16x16x32_bf16 v[116:119], v[140:143], v[168:171], v[116:119]
	v_mfma_f32_16x16x32_bf16 v[108:111], v[152:155], v[168:171], v[108:111]
	v_mfma_f32_16x16x32_bf16 v[100:103], v[140:143], v[176:179], v[100:103]
	v_mfma_f32_16x16x32_bf16 v[92:95], v[152:155], v[176:179], v[92:95]
	v_mfma_f32_16x16x32_bf16 v[84:87], v[140:143], v[184:187], v[84:87]
	v_mfma_f32_16x16x32_bf16 v[76:79], v[152:155], v[184:187], v[76:79]
	v_mfma_f32_16x16x32_bf16 v[124:127], v[148:151], v[164:167], v[124:127]
	v_mfma_f32_16x16x32_bf16 v[120:123], v[156:159], v[164:167], v[120:123]
	v_mfma_f32_16x16x32_bf16 v[116:119], v[148:151], v[172:175], v[116:119]
	v_mfma_f32_16x16x32_bf16 v[108:111], v[156:159], v[172:175], v[108:111]
	v_mfma_f32_16x16x32_bf16 v[100:103], v[148:151], v[180:183], v[100:103]
	v_mfma_f32_16x16x32_bf16 v[92:95], v[156:159], v[180:183], v[92:95]
	v_mfma_f32_16x16x32_bf16 v[84:87], v[148:151], v[188:191], v[84:87]
	v_mfma_f32_16x16x32_bf16 v[76:79], v[156:159], v[188:191], v[76:79]
	s_barrier
	s_add_i32 s0, s85, 0x100
	s_add_i32 s1, s1, s24
	ds_read_b128 v[192:195], v208 offset:16384
	ds_read_b128 v[196:199], v208 offset:17408
	ds_read_b128 v[200:203], v208 offset:18432
	ds_read_b128 v[204:207], v208 offset:19456
	s_mov_b32 m0, s1
	s_nop 0
	global_load_lds_dwordx4 v146, s[72:73]
	s_add_i32 m0, s1, 0x2000
	s_nop 0
	global_load_lds_dwordx4 v128, s[72:73]
	s_barrier
	s_waitcnt lgkmcnt(0)
	v_mfma_f32_16x16x32_bf16 v[112:115], v[192:195], v[160:163], v[112:115]
	v_mfma_f32_16x16x32_bf16 v[104:107], v[200:203], v[160:163], v[104:107]
	v_mfma_f32_16x16x32_bf16 v[96:99], v[192:195], v[168:171], v[96:99]
	v_mfma_f32_16x16x32_bf16 v[88:91], v[200:203], v[168:171], v[88:91]
	v_mfma_f32_16x16x32_bf16 v[80:83], v[192:195], v[176:179], v[80:83]
	v_mfma_f32_16x16x32_bf16 v[72:75], v[200:203], v[176:179], v[72:75]
	v_mfma_f32_16x16x32_bf16 v[68:71], v[192:195], v[184:187], v[68:71]
	v_mfma_f32_16x16x32_bf16 v[64:67], v[200:203], v[184:187], v[64:67]
	v_mfma_f32_16x16x32_bf16 v[112:115], v[196:199], v[164:167], v[112:115]
	v_mfma_f32_16x16x32_bf16 v[104:107], v[204:207], v[164:167], v[104:107]
	v_mfma_f32_16x16x32_bf16 v[96:99], v[196:199], v[172:175], v[96:99]
	v_mfma_f32_16x16x32_bf16 v[88:91], v[204:207], v[172:175], v[88:91]
	v_mfma_f32_16x16x32_bf16 v[80:83], v[196:199], v[180:183], v[80:83]
	v_mfma_f32_16x16x32_bf16 v[72:75], v[204:207], v[180:183], v[72:75]
	v_mfma_f32_16x16x32_bf16 v[68:71], v[196:199], v[188:191], v[68:71]
	v_mfma_f32_16x16x32_bf16 v[64:67], v[204:207], v[188:191], v[64:67]
	s_mov_b32 m0, s25
	s_barrier
	ds_read_b128 v[160:163], v139 offset:16384
	ds_read_b128 v[164:167], v139 offset:17408
	ds_read_b128 v[168:171], v139 offset:18432
	ds_read_b128 v[172:175], v139 offset:19456
	ds_read_b128 v[176:179], v139 offset:20480
	ds_read_b128 v[180:183], v139 offset:21504
	ds_read_b128 v[184:187], v139 offset:22528
	ds_read_b128 v[188:191], v139 offset:23552
	global_load_lds_dwordx4 v132, s[70:71]
	s_mov_b32 m0, s36
	s_nop 0
	global_load_lds_dwordx4 v130, s[70:71]
	s_barrier
	s_waitcnt lgkmcnt(0)
	v_mfma_f32_16x16x32_bf16 v[60:63], v[140:143], v[160:163], v[60:63]
	v_mfma_f32_16x16x32_bf16 v[56:59], v[152:155], v[160:163], v[56:59]
	v_mfma_f32_16x16x32_bf16 v[52:55], v[140:143], v[168:171], v[52:55]
	v_mfma_f32_16x16x32_bf16 v[44:47], v[152:155], v[168:171], v[44:47]
	v_mfma_f32_16x16x32_bf16 v[36:39], v[140:143], v[176:179], v[36:39]
	v_mfma_f32_16x16x32_bf16 v[28:31], v[152:155], v[176:179], v[28:31]
	v_mfma_f32_16x16x32_bf16 v[20:23], v[140:143], v[184:187], v[20:23]
	v_mfma_f32_16x16x32_bf16 v[12:15], v[152:155], v[184:187], v[12:15]
	v_mfma_f32_16x16x32_bf16 v[60:63], v[148:151], v[164:167], v[60:63]
	v_mfma_f32_16x16x32_bf16 v[56:59], v[156:159], v[164:167], v[56:59]
	v_mfma_f32_16x16x32_bf16 v[52:55], v[148:151], v[172:175], v[52:55]
	v_mfma_f32_16x16x32_bf16 v[44:47], v[156:159], v[172:175], v[44:47]
	v_mfma_f32_16x16x32_bf16 v[36:39], v[148:151], v[180:183], v[36:39]
	v_mfma_f32_16x16x32_bf16 v[28:31], v[156:159], v[180:183], v[28:31]
	v_mfma_f32_16x16x32_bf16 v[20:23], v[148:151], v[188:191], v[20:23]
	v_mfma_f32_16x16x32_bf16 v[12:15], v[156:159], v[188:191], v[12:15]
	s_barrier
	s_add_u32 s72, s72, 0x20000
	s_addc_u32 s73, s73, 0
	s_add_i32 s0, s0, s24
	s_mov_b32 m0, s0
	s_nop 0
	global_load_lds_dwordx4 v146, s[72:73]
	s_add_i32 m0, s0, 0x2000
	s_nop 0
	global_load_lds_dwordx4 v128, s[72:73]
	s_waitcnt vmcnt(6)
	s_barrier
; #define G_STAGE(bufoff, gbase, voff) do { _Pragma("unroll") for (int _i = 0; _i < 2; ++_i) \
;         __builtin_amdgcn_global_load_lds((const unsigned*)((const char*)(gbase) + (voff)[_i]), (LAS unsigned*)(lds + (bufoff) + ldsw + _i * 8192), 16, 0, 0); } while (0)
; #define G_LDA(dst, b, h) do { _Pragma("unroll") for (int m = 0; m < 4; ++m) _Pragma("unroll") for (int k = 0; k < 2; ++k) dst[m][k] = *(const LAS bf16x8*)(lds + G_SA(b, h) + aoff + m * 2048 + k * 1024); } while (0)
; #define G_LDB(dst, b, h) do { _Pragma("unroll") for (int n = 0; n < 2; ++n) _Pragma("unroll") for (int k = 0; k < 2; ++k) dst[n][k] = *(const LAS bf16x8*)(lds + G_SB(b, h) + boff + n * 2048 + k * 1024); } while (0)
; #define G_MMA(ai, bj, At, Bt) do { __builtin_amdgcn_s_setprio(1); _Pragma("unroll") for (int m = 0; m < 4; ++m) _Pragma("unroll") for (int n = 0; n < 2; ++n) _Pragma("unroll") for (int k = 0; k < 2; ++k) \
;         acc[ai][bj][m][n] = __builtin_amdgcn_mfma_f32_16x16x32_bf16(Bt[n][k], At[m][k], acc[ai][bj][m][n], 0, 0, 0); __builtin_amdgcn_s_setprio(0); } while (0)
; #define G_WAIT_V(n) asm volatile("s_waitcnt vmcnt(" #n ")" ::: "memory")
; #define G_WAIT_L(n) asm volatile("s_waitcnt lgkmcnt(" #n ")" ::: "memory")
; #define G_BAR __builtin_amdgcn_s_barrier()
; #define G_SCHED __builtin_amdgcn_sched_barrier(0)
; template <class J>
; DI void gemm_phase(LAS unsigned char* lds, const J& job) {
;     ...
;       G_WAIT_V(6); G_BAR; G_MMA(1, 1, At, B1); G_BAR;
;       G_LDB(B0, 1, 0); G_SCHED; G_LDA(At, 1, 0); G_STAGE(G_SA(0, 1), a2 + hstepA, voffA);
;       G_WAIT_L(8); G_BAR; G_WAIT_L(0); G_MMA(0, 0, At, B0); G_BAR; G_SCHED;
;       G_LDB(B1, 1, 1); G_STAGE(G_SB(1, 0), b3, voffB);
;       G_BAR; G_WAIT_L(0); G_MMA(0, 1, At, B1); G_BAR;
;       G_LDA(At, 1, 1); G_STAGE(G_SA(1, 0), a3, voffA);
;       G_BAR; G_WAIT_L(0); G_MMA(1, 0, At, B0); G_BAR; G_SCHED;
	v_mfma_f32_16x16x32_bf16 v[48:51], v[192:195], v[160:163], v[48:51]
	v_mfma_f32_16x16x32_bf16 v[40:43], v[200:203], v[160:163], v[40:43]
	v_mfma_f32_16x16x32_bf16 v[32:35], v[192:195], v[168:171], v[32:35]
	v_mfma_f32_16x16x32_bf16 v[24:27], v[200:203], v[168:171], v[24:27]
	v_mfma_f32_16x16x32_bf16 v[16:19], v[192:195], v[176:179], v[16:19]
	v_mfma_f32_16x16x32_bf16 v[8:11], v[200:203], v[176:179], v[8:11]
	v_mfma_f32_16x16x32_bf16 v[4:7], v[192:195], v[184:187], v[4:7]
	v_mfma_f32_16x16x32_bf16 v[0:3], v[200:203], v[184:187], v[0:3]
	v_mfma_f32_16x16x32_bf16 v[48:51], v[196:199], v[164:167], v[48:51]
	v_mfma_f32_16x16x32_bf16 v[40:43], v[204:207], v[164:167], v[40:43]
	v_mfma_f32_16x16x32_bf16 v[32:35], v[196:199], v[172:175], v[32:35]
	v_mfma_f32_16x16x32_bf16 v[24:27], v[204:207], v[172:175], v[24:27]
	v_mfma_f32_16x16x32_bf16 v[16:19], v[196:199], v[180:183], v[16:19]
	v_mfma_f32_16x16x32_bf16 v[8:11], v[204:207], v[180:183], v[8:11]
	v_mfma_f32_16x16x32_bf16 v[4:7], v[196:199], v[188:191], v[4:7]
	v_mfma_f32_16x16x32_bf16 v[0:3], v[204:207], v[188:191], v[0:3]
	s_add_i32 s0, s88, 0x100
	s_barrier
	ds_read_b128 v[140:143], v208 offset:32768
	ds_read_b128 v[148:151], v208 offset:33792
	ds_read_b128 v[152:155], v208 offset:34816
	ds_read_b128 v[156:159], v208 offset:35840
	s_add_u32 s70, s70, 0x80000
	s_addc_u32 s71, s71, 0
	s_mov_b32 m0, s37
	ds_read_b128 v[160:163], v139 offset:32768
	ds_read_b128 v[164:167], v139 offset:33792
	ds_read_b128 v[168:171], v139 offset:34816
	ds_read_b128 v[172:175], v139 offset:35840
	ds_read_b128 v[176:179], v139 offset:36864
	ds_read_b128 v[180:183], v139 offset:37888
	ds_read_b128 v[184:187], v139 offset:38912
	ds_read_b128 v[188:191], v139 offset:39936
	global_load_lds_dwordx4 v132, s[70:71]
	s_mov_b32 m0, s38
	s_nop 0
	global_load_lds_dwordx4 v130, s[70:71]
	s_waitcnt lgkmcnt(8)
	s_barrier
	s_waitcnt lgkmcnt(0)
	v_mfma_f32_16x16x32_bf16 v[124:127], v[140:143], v[160:163], v[124:127]
	v_mfma_f32_16x16x32_bf16 v[120:123], v[152:155], v[160:163], v[120:123]
	v_mfma_f32_16x16x32_bf16 v[116:119], v[140:143], v[168:171], v[116:119]
	v_mfma_f32_16x16x32_bf16 v[108:111], v[152:155], v[168:171], v[108:111]
	v_mfma_f32_16x16x32_bf16 v[100:103], v[140:143], v[176:179], v[100:103]
	v_mfma_f32_16x16x32_bf16 v[92:95], v[152:155], v[176:179], v[92:95]
	v_mfma_f32_16x16x32_bf16 v[84:87], v[140:143], v[184:187], v[84:87]
	v_mfma_f32_16x16x32_bf16 v[76:79], v[152:155], v[184:187], v[76:79]
	v_mfma_f32_16x16x32_bf16 v[124:127], v[148:151], v[164:167], v[124:127]
	v_mfma_f32_16x16x32_bf16 v[120:123], v[156:159], v[164:167], v[120:123]
	v_mfma_f32_16x16x32_bf16 v[116:119], v[148:151], v[172:175], v[116:119]
	v_mfma_f32_16x16x32_bf16 v[108:111], v[156:159], v[172:175], v[108:111]
	v_mfma_f32_16x16x32_bf16 v[100:103], v[148:151], v[180:183], v[100:103]
	v_mfma_f32_16x16x32_bf16 v[92:95], v[156:159], v[180:183], v[92:95]
	v_mfma_f32_16x16x32_bf16 v[84:87], v[148:151], v[188:191], v[84:87]
	v_mfma_f32_16x16x32_bf16 v[76:79], v[156:159], v[188:191], v[76:79]
	s_barrier
	s_add_i32 s1, s89, 0x100
	s_add_i32 s0, s0, s24
	ds_read_b128 v[192:195], v208 offset:49152
	ds_read_b128 v[196:199], v208 offset:50176
	ds_read_b128 v[200:203], v208 offset:51200
	ds_read_b128 v[204:207], v208 offset:52224
	s_mov_b32 m0, s0
	s_nop 0
	global_load_lds_dwordx4 v146, s[66:67]
	s_add_i32 m0, s0, 0x2000
	s_nop 0
	global_load_lds_dwordx4 v128, s[66:67]
	s_barrier
	s_waitcnt lgkmcnt(0)
	v_mfma_f32_16x16x32_bf16 v[112:115], v[192:195], v[160:163], v[112:115]
	v_mfma_f32_16x16x32_bf16 v[104:107], v[200:203], v[160:163], v[104:107]
	v_mfma_f32_16x16x32_bf16 v[96:99], v[192:195], v[168:171], v[96:99]
	v_mfma_f32_16x16x32_bf16 v[88:91], v[200:203], v[168:171], v[88:91]
	v_mfma_f32_16x16x32_bf16 v[80:83], v[192:195], v[176:179], v[80:83]
	v_mfma_f32_16x16x32_bf16 v[72:75], v[200:203], v[176:179], v[72:75]
	v_mfma_f32_16x16x32_bf16 v[68:71], v[192:195], v[184:187], v[68:71]
	v_mfma_f32_16x16x32_bf16 v[64:67], v[200:203], v[184:187], v[64:67]
	v_mfma_f32_16x16x32_bf16 v[112:115], v[196:199], v[164:167], v[112:115]
	v_mfma_f32_16x16x32_bf16 v[104:107], v[204:207], v[164:167], v[104:107]
	v_mfma_f32_16x16x32_bf16 v[96:99], v[196:199], v[172:175], v[96:99]
	v_mfma_f32_16x16x32_bf16 v[88:91], v[204:207], v[172:175], v[88:91]
	v_mfma_f32_16x16x32_bf16 v[80:83], v[196:199], v[180:183], v[80:83]
	v_mfma_f32_16x16x32_bf16 v[72:75], v[204:207], v[180:183], v[72:75]
	v_mfma_f32_16x16x32_bf16 v[68:71], v[196:199], v[188:191], v[68:71]
	v_mfma_f32_16x16x32_bf16 v[64:67], v[204:207], v[188:191], v[64:67]
	s_mov_b32 m0, s75
	s_barrier
	ds_read_b128 v[160:163], v139 offset:49152
	ds_read_b128 v[164:167], v139 offset:50176
	ds_read_b128 v[168:171], v139 offset:51200
	ds_read_b128 v[172:175], v139 offset:52224
	ds_read_b128 v[176:179], v139 offset:53248
	ds_read_b128 v[180:183], v139 offset:54272
	ds_read_b128 v[184:187], v139 offset:55296
	ds_read_b128 v[188:191], v139 offset:56320
	global_load_lds_dwordx4 v132, s[68:69]
	s_mov_b32 m0, s76
	s_nop 0
	global_load_lds_dwordx4 v130, s[68:69]
	s_barrier
	s_waitcnt lgkmcnt(0)
	v_mfma_f32_16x16x32_bf16 v[60:63], v[140:143], v[160:163], v[60:63]
	v_mfma_f32_16x16x32_bf16 v[56:59], v[152:155], v[160:163], v[56:59]
	v_mfma_f32_16x16x32_bf16 v[52:55], v[140:143], v[168:171], v[52:55]
	v_mfma_f32_16x16x32_bf16 v[44:47], v[152:155], v[168:171], v[44:47]
	v_mfma_f32_16x16x32_bf16 v[36:39], v[140:143], v[176:179], v[36:39]
	v_mfma_f32_16x16x32_bf16 v[28:31], v[152:155], v[176:179], v[28:31]
	v_mfma_f32_16x16x32_bf16 v[20:23], v[140:143], v[184:187], v[20:23]
	v_mfma_f32_16x16x32_bf16 v[12:15], v[152:155], v[184:187], v[12:15]
	v_mfma_f32_16x16x32_bf16 v[60:63], v[148:151], v[164:167], v[60:63]
	v_mfma_f32_16x16x32_bf16 v[56:59], v[156:159], v[164:167], v[56:59]
	v_mfma_f32_16x16x32_bf16 v[52:55], v[148:151], v[172:175], v[52:55]
	v_mfma_f32_16x16x32_bf16 v[44:47], v[156:159], v[172:175], v[44:47]
	v_mfma_f32_16x16x32_bf16 v[36:39], v[148:151], v[180:183], v[36:39]
	v_mfma_f32_16x16x32_bf16 v[28:31], v[156:159], v[180:183], v[28:31]
	v_mfma_f32_16x16x32_bf16 v[20:23], v[148:151], v[188:191], v[20:23]
	v_mfma_f32_16x16x32_bf16 v[12:15], v[156:159], v[188:191], v[12:15]
	s_barrier
; #define G_STAGE(bufoff, gbase, voff) do { _Pragma("unroll") for (int _i = 0; _i < 2; ++_i) \
;         __builtin_amdgcn_global_load_lds((const unsigned*)((const char*)(gbase) + (voff)[_i]), (LAS unsigned*)(lds + (bufoff) + ldsw + _i * 8192), 16, 0, 0); } while (0)
; #define G_LDA(dst, b, h) do { _Pragma("unroll") for (int m = 0; m < 4; ++m) _Pragma("unroll") for (int k = 0; k < 2; ++k) dst[m][k] = *(const LAS bf16x8*)(lds + G_SA(b, h) + aoff + m * 2048 + k * 1024); } while (0)
; #define G_LDB(dst, b, h) do { _Pragma("unroll") for (int n = 0; n < 2; ++n) _Pragma("unroll") for (int k = 0; k < 2; ++k) dst[n][k] = *(const LAS bf16x8*)(lds + G_SB(b, h) + boff + n * 2048 + k * 1024); } while (0)
; #define G_WAIT_V(n) asm volatile("s_waitcnt vmcnt(" #n ")" ::: "memory")
; #define G_WAIT_L(n) asm volatile("s_waitcnt lgkmcnt(" #n ")" ::: "memory")
; #define G_BAR __builtin_amdgcn_s_barrier()
; #define G_SCHED __builtin_amdgcn_sched_barrier(0)
; template <class J>
; DI void gemm_phase(LAS unsigned char* lds, const J& job) {
;     ...
;       const bool last = (t == nt - 2);
;       const char* a1 = cA + G_KT(t + 1);
;       const char* a2 = last ? nA + G_KT(0) : cA + G_KT(t + 2); const char* b2 = last ? nB + G_KT(0) : cB + G_KT(t + 2);
;       const char* a3 = last ? nA + G_KT(1) : cA + G_KT(t + 3); const char* b3 = last ? nB + G_KT(1) : cB + G_KT(t + 3);
;       G_LDB(B0, 0, 0); G_SCHED; G_LDA(At, 0, 0); G_STAGE(G_SA(1, 1), a1 + hstepA, voffA);
;       G_WAIT_L(8); G_BAR; G_WAIT_L(0); G_MMA(0, 0, At, B0); G_BAR; G_SCHED;
;       G_LDB(B1, 0, 1); G_STAGE(G_SB(0, 0), b2, voffB);
;       G_BAR; G_WAIT_L(0); G_MMA(0, 1, At, B1); G_BAR;
;       G_LDA(At, 0, 1); G_STAGE(G_SA(0, 0), a2, voffA);
;       G_BAR; G_WAIT_L(0); G_MMA(1, 0, At, B0); G_BAR; G_SCHED;
;       G_STAGE(G_SB(0, 1), b2 + hstepB, voffB);
;       G_WAIT_V(6); G_BAR; G_MMA(1, 1, At, B1); G_BAR;
;       G_LDB(B0, 1, 0); G_SCHED; G_LDA(At, 1, 0); G_STAGE(G_SA(0, 1), a2 + hstepA, voffA);
;       G_WAIT_L(8); G_BAR; G_WAIT_L(0); G_MMA(0, 0, At, B0); G_BAR; G_SCHED;
;       G_LDB(B1, 1, 1); G_STAGE(G_SB(1, 0), b3, voffB);
;       G_BAR; G_WAIT_L(0); G_MMA(0, 1, At, B1); G_BAR;
;       G_LDA(At, 1, 1); G_STAGE(G_SA(1, 0), a3, voffA);
;       G_BAR; G_WAIT_L(0); G_MMA(1, 0, At, B0); G_BAR; G_SCHED;
;       G_STAGE(G_SB(1, 1), b3 + hstepB, voffB);
;       G_WAIT_V(6); G_BAR; G_MMA(1, 1, At, B1); G_BAR;
	s_add_u32 s66, s66, 0x20000
	s_addc_u32 s67, s67, 0
	s_add_i32 s0, s1, s24
	s_mov_b32 m0, s0
	s_nop 0
	global_load_lds_dwordx4 v146, s[66:67]
	s_add_i32 m0, s0, 0x2000
	s_nop 0
	global_load_lds_dwordx4 v128, s[66:67]
	s_add_i32 s6, s6, 2
	s_addk_i32 s56, 0x100
	s_addk_i32 s7, 0x100
	s_add_i32 s1, s56, 0xffffff80
	s_and_b32 s0, s7, 0x380
	s_and_b32 s1, s1, 0x380
	s_add_u32 s57, s64, s1
	s_addc_u32 s66, s65, 0
	s_add_u32 s1, s62, s1
	s_addc_u32 s67, s63, 0
	s_and_b32 s68, s56, 0x380
	s_add_u32 s80, s64, s68
	s_addc_u32 s69, s65, 0
	s_add_u32 s97, s62, s68
	s_addc_u32 vcc_lo, s63, 0
	s_cmp_eq_u32 s6, 4
	s_cselect_b32 s71, s83, s66
	s_cselect_b32 s70, s47, s57
	s_cselect_b32 s73, s87, s67
	s_cselect_b32 s72, s86, s1
	s_cselect_b32 s69, s94, s69
	s_cselect_b32 s68, s33, s80
	s_cselect_b32 s67, s5, vcc_lo
	s_cselect_b32 s66, s96, s97
	s_waitcnt vmcnt(6)
	s_barrier
	v_mfma_f32_16x16x32_bf16 v[48:51], v[192:195], v[160:163], v[48:51]
	v_mfma_f32_16x16x32_bf16 v[40:43], v[200:203], v[160:163], v[40:43]
	v_mfma_f32_16x16x32_bf16 v[32:35], v[192:195], v[168:171], v[32:35]
	v_mfma_f32_16x16x32_bf16 v[24:27], v[200:203], v[168:171], v[24:27]
	v_mfma_f32_16x16x32_bf16 v[16:19], v[192:195], v[176:179], v[16:19]
	v_mfma_f32_16x16x32_bf16 v[8:11], v[200:203], v[176:179], v[8:11]
	v_mfma_f32_16x16x32_bf16 v[4:7], v[192:195], v[184:187], v[4:7]
	v_mfma_f32_16x16x32_bf16 v[0:3], v[200:203], v[184:187], v[0:3]
	v_mfma_f32_16x16x32_bf16 v[48:51], v[196:199], v[164:167], v[48:51]
	v_mfma_f32_16x16x32_bf16 v[40:43], v[204:207], v[164:167], v[40:43]
	v_mfma_f32_16x16x32_bf16 v[32:35], v[196:199], v[172:175], v[32:35]
	v_mfma_f32_16x16x32_bf16 v[24:27], v[204:207], v[172:175], v[24:27]
	v_mfma_f32_16x16x32_bf16 v[16:19], v[196:199], v[180:183], v[16:19]
	v_mfma_f32_16x16x32_bf16 v[8:11], v[204:207], v[180:183], v[8:11]
	v_mfma_f32_16x16x32_bf16 v[4:7], v[196:199], v[188:191], v[4:7]
	v_mfma_f32_16x16x32_bf16 v[0:3], v[204:207], v[188:191], v[0:3]
	s_cmp_gt_u32 s6, 5
	s_barrier
	s_cbranch_scc0 .LBB0_104
; DI unsigned pk2(float lo, float hi) { unsigned r; asm("v_cvt_pk_bf16_f32 %0, %1, %2" : "=v"(r) : "v"(lo), "v"(hi)); return r; }
; #define G_WAIT_V(n) asm volatile("s_waitcnt vmcnt(" #n ")" ::: "memory")
; #define G_BAR __builtin_amdgcn_s_barrier()
; template <class J>
; DI void gemm_phase(LAS unsigned char* lds, const J& job) {
;     ...
;     if (!has_next) break;
; #pragma unroll
;     for (int a = 0; a < 2; ++a)
; #pragma unroll
;       for (int b = 0; b < 2; ++b)
; #pragma unroll
;         for (int m = 0; m < 4; ++m)
; #pragma unroll
;           for (int n = 0; n < 2; ++n) acc[a][b][m][n] = (f32x4){0.f, 0.f, 0.f, 0.f};
;     cur = nxt; cA = nA; cB = nB; ++ui;
;   }
;   G_WAIT_V(0);
;   if (wr == 0) G_BAR;
;   G_BAR;
;   DI void epi(const Acc& acc, const Unit& u, int wr, int wc, int fr, int fq) const {
; #pragma unroll
;     for (int ai = 0; ai < 2; ++ai)
; #pragma unroll
;       for (int m = 0; m < 4; ++m) {
;         const int row = u.pm * 256 + ai * HALF + wr * 64 + m * 16 + fr;
; #pragma unroll
;         for (int bj = 0; bj < 2; ++bj) {
;           const int col = u.pn * 256 + bj * HALF + wc * 32 + 8 * fq;
;           const f32x4 v0 = acc[ai][bj][m][0], v1 = acc[ai][bj][m][1];
;           u32x4 o; o.x = pk2(v0.x, v0.y); o.y = pk2(v0.z, v0.w); o.z = pk2(v1.x, v1.y); o.w = pk2(v1.z, v1.w);
;           *(u32x4*)(Z + (size_t)row * NGATE + col) = o;
;         }
;       }
;   }
	v_mov_b32_e32 v135, v137
	v_mov_b32_e32 v134, v136
	s_lshl_b32 s0, s22, 8
	s_add_i32 s0, s0, s44
	v_add_u32_e32 v134, s0, v134
	s_lshl_b32 s0, s46, 8
	s_or_b32 s0, s0, s45
	v_cvt_pk_bf16_f32 v68, v68, v69
	v_cvt_pk_bf16_f32 v69, v70, v71
	v_cvt_pk_bf16_f32 v70, v64, v65
	v_add_u32_e32 v64, 0x80, v134
	v_lshl_add_u32 v140, v135, 3, s0
	v_ashrrev_i32_e32 v135, 31, v134
	v_ashrrev_i32_e32 v65, 31, v64
	v_lshlrev_b64 v[142:143], 14, v[134:135]
	v_ashrrev_i32_e32 v141, 31, v140
	v_lshlrev_b64 v[64:65], 14, v[64:65]
	v_cvt_pk_bf16_f32 v124, v124, v125
	v_cvt_pk_bf16_f32 v125, v126, v127
	v_cvt_pk_bf16_f32 v126, v120, v121
	v_cvt_pk_bf16_f32 v127, v122, v123
	v_lshl_add_u64 v[122:123], s[26:27], 0, v[142:143]
	v_lshlrev_b64 v[120:121], 1, v[140:141]
	v_cvt_pk_bf16_f32 v112, v112, v113
	v_cvt_pk_bf16_f32 v113, v114, v115
	v_cvt_pk_bf16_f32 v114, v104, v105
	v_add_u32_e32 v104, 16, v134
	v_cvt_pk_bf16_f32 v60, v60, v61
	v_cvt_pk_bf16_f32 v61, v62, v63
	v_cvt_pk_bf16_f32 v62, v56, v57
	v_lshl_add_u64 v[56:57], s[26:27], 0, v[64:65]
	v_cvt_pk_bf16_f32 v48, v48, v49
	v_cvt_pk_bf16_f32 v49, v50, v51
	v_cvt_pk_bf16_f32 v50, v40, v41
	v_add_u32_e32 v40, 0x90, v134
	v_lshl_add_u64 v[122:123], v[122:123], 0, v[120:121]
	v_ashrrev_i32_e32 v105, 31, v104
	v_lshl_add_u64 v[56:57], v[56:57], 0, v[120:121]
	v_ashrrev_i32_e32 v41, 31, v40
	v_cvt_pk_bf16_f32 v115, v106, v107
	global_store_dwordx4 v[122:123], v[112:115], off offset:256
	v_cvt_pk_bf16_f32 v51, v42, v43
	global_store_dwordx4 v[56:57], v[48:51], off offset:256
	v_cvt_pk_bf16_f32 v106, v108, v109
	v_cvt_pk_bf16_f32 v96, v96, v97
	v_cvt_pk_bf16_f32 v97, v98, v99
	s_nop 0
	v_lshlrev_b64 v[112:113], 14, v[104:105]
	v_lshl_add_u64 v[108:109], s[26:27], 0, v[112:113]
	v_lshlrev_b64 v[48:49], 14, v[40:41]
	v_cvt_pk_bf16_f32 v98, v88, v89
	v_add_u32_e32 v88, 32, v134
	v_cvt_pk_bf16_f32 v42, v44, v45
	v_lshl_add_u64 v[44:45], s[26:27], 0, v[48:49]
	v_cvt_pk_bf16_f32 v32, v32, v33
	v_cvt_pk_bf16_f32 v33, v34, v35
	v_cvt_pk_bf16_f32 v34, v24, v25
	v_add_u32_e32 v24, 0xa0, v134
	v_lshl_add_u64 v[108:109], v[108:109], 0, v[120:121]
	v_ashrrev_i32_e32 v89, 31, v88
	v_lshl_add_u64 v[44:45], v[44:45], 0, v[120:121]
	v_ashrrev_i32_e32 v25, 31, v24
	v_cvt_pk_bf16_f32 v99, v90, v91
	global_store_dwordx4 v[108:109], v[96:99], off offset:256
	v_cvt_pk_bf16_f32 v35, v26, v27
	global_store_dwordx4 v[44:45], v[32:35], off offset:256
	v_cvt_pk_bf16_f32 v90, v92, v93
	v_cvt_pk_bf16_f32 v80, v80, v81
	v_cvt_pk_bf16_f32 v81, v82, v83
	s_nop 0
	v_lshlrev_b64 v[96:97], 14, v[88:89]
	v_lshl_add_u64 v[92:93], s[26:27], 0, v[96:97]
	v_lshlrev_b64 v[32:33], 14, v[24:25]
	v_cvt_pk_bf16_f32 v82, v72, v73
	v_add_u32_e32 v72, 48, v134
	v_cvt_pk_bf16_f32 v26, v28, v29
	v_lshl_add_u64 v[28:29], s[26:27], 0, v[32:33]
	v_cvt_pk_bf16_f32 v16, v16, v17
	v_cvt_pk_bf16_f32 v17, v18, v19
	v_cvt_pk_bf16_f32 v18, v8, v9
	v_add_u32_e32 v8, 0xb0, v134
	v_lshl_add_u64 v[92:93], v[92:93], 0, v[120:121]
	v_ashrrev_i32_e32 v73, 31, v72
	v_lshl_add_u64 v[28:29], v[28:29], 0, v[120:121]
	v_ashrrev_i32_e32 v9, 31, v8
	v_cvt_pk_bf16_f32 v83, v74, v75
	global_store_dwordx4 v[92:93], v[80:83], off offset:256
	v_cvt_pk_bf16_f32 v19, v10, v11
	global_store_dwordx4 v[28:29], v[16:19], off offset:256
	v_cvt_pk_bf16_f32 v74, v76, v77
	v_cvt_pk_bf16_f32 v10, v12, v13
	s_and_b64 vcc, exec, s[12:13]
	v_lshlrev_b64 v[80:81], 14, v[72:73]
	v_lshlrev_b64 v[16:17], 14, v[8:9]
	v_lshl_add_u64 v[76:77], s[26:27], 0, v[80:81]
	v_lshl_add_u64 v[12:13], s[26:27], 0, v[16:17]
	v_lshl_add_u64 v[76:77], v[76:77], 0, v[120:121]
	v_lshl_add_u64 v[12:13], v[12:13], 0, v[120:121]
	s_mov_b32 s46, s8
	s_mov_b32 s22, s16
	s_mov_b64 s[62:63], s[20:21]
	s_mov_b64 s[64:65], s[18:19]
	global_store_dwordx4 v[122:123], v[124:127], off
	v_cvt_pk_bf16_f32 v104, v116, v117
	v_cvt_pk_bf16_f32 v105, v118, v119
	v_cvt_pk_bf16_f32 v107, v110, v111
	global_store_dwordx4 v[108:109], v[104:107], off
	v_cvt_pk_bf16_f32 v88, v100, v101
	v_cvt_pk_bf16_f32 v89, v102, v103
	v_cvt_pk_bf16_f32 v91, v94, v95
	global_store_dwordx4 v[92:93], v[88:91], off
	v_cvt_pk_bf16_f32 v72, v84, v85
	v_cvt_pk_bf16_f32 v73, v86, v87
	v_cvt_pk_bf16_f32 v75, v78, v79
	global_store_dwordx4 v[76:77], v[72:75], off
	v_cvt_pk_bf16_f32 v71, v66, v67
	global_store_dwordx4 v[76:77], v[68:71], off offset:256
	v_cvt_pk_bf16_f32 v63, v58, v59
	global_store_dwordx4 v[56:57], v[60:63], off
	v_cvt_pk_bf16_f32 v40, v52, v53
	v_cvt_pk_bf16_f32 v41, v54, v55
	v_cvt_pk_bf16_f32 v43, v46, v47
	global_store_dwordx4 v[44:45], v[40:43], off
	v_cvt_pk_bf16_f32 v24, v36, v37
	v_cvt_pk_bf16_f32 v25, v38, v39
	v_cvt_pk_bf16_f32 v27, v30, v31
	global_store_dwordx4 v[28:29], v[24:27], off
	v_cvt_pk_bf16_f32 v8, v20, v21
	v_cvt_pk_bf16_f32 v9, v22, v23
	v_cvt_pk_bf16_f32 v11, v14, v15
	global_store_dwordx4 v[12:13], v[8:11], off
	v_cvt_pk_bf16_f32 v4, v4, v5
	v_cvt_pk_bf16_f32 v5, v6, v7
	v_cvt_pk_bf16_f32 v6, v0, v1
	v_cvt_pk_bf16_f32 v7, v2, v3
	global_store_dwordx4 v[12:13], v[4:7], off offset:256
	s_cbranch_vccz .LBB0_101
	s_setprio 0
	s_waitcnt vmcnt(0)
	v_readlane_b32 s44, v255, 6
	s_cmpk_gt_u32 s4, 0xff
	v_readlane_b32 s45, v255, 7
	s_cbranch_scc1 .LBB0_108
	s_barrier

; #define G_STAGE(bufoff, gbase, voff) do { _Pragma("unroll") for (int _i = 0; _i < 2; ++_i) \
;         __builtin_amdgcn_global_load_lds((const unsigned*)((const char*)(gbase) + (voff)[_i]), (LAS unsigned*)(lds + (bufoff) + ldsw + _i * 8192), 16, 0, 0); } while (0)
; #define G_LDA(dst, b, h) do { _Pragma("unroll") for (int m = 0; m < 4; ++m) _Pragma("unroll") for (int k = 0; k < 2; ++k) dst[m][k] = *(const LAS bf16x8*)(lds + G_SA(b, h) + aoff + m * 2048 + k * 1024); } while (0)
; #define G_LDB(dst, b, h) do { _Pragma("unroll") for (int n = 0; n < 2; ++n) _Pragma("unroll") for (int k = 0; k < 2; ++k) dst[n][k] = *(const LAS bf16x8*)(lds + G_SB(b, h) + boff + n * 2048 + k * 1024); } while (0)
; #define G_MMA(ai, bj, At, Bt) do { __builtin_amdgcn_s_setprio(1); _Pragma("unroll") for (int m = 0; m < 4; ++m) _Pragma("unroll") for (int n = 0; n < 2; ++n) _Pragma("unroll") for (int k = 0; k < 2; ++k) \
;         acc[ai][bj][m][n] = __builtin_amdgcn_mfma_f32_16x16x32_bf16(Bt[n][k], At[m][k], acc[ai][bj][m][n], 0, 0, 0); __builtin_amdgcn_s_setprio(0); } while (0)
; #define G_WAIT_V(n) asm volatile("s_waitcnt vmcnt(" #n ")" ::: "memory")
; #define G_WAIT_L(n) asm volatile("s_waitcnt lgkmcnt(" #n ")" ::: "memory")
; #define G_BAR __builtin_amdgcn_s_barrier()
; #define G_SCHED __builtin_amdgcn_sched_barrier(0)
; template <class J>
; DI void gemm_phase(LAS unsigned char* lds, const J& job) {
;     ...
;       G_LDB(B0, 0, 0); G_SCHED; G_LDA(At, 0, 0); G_STAGE(G_SA(1, 1), a1 + hstepA, voffA);
;       G_WAIT_L(8); G_BAR; G_WAIT_L(0); G_MMA(0, 0, At, B0); G_BAR; G_SCHED;
;       G_LDB(B1, 0, 1); G_STAGE(G_SB(0, 0), b2, voffB);
;       G_BAR; G_WAIT_L(0); G_MMA(0, 1, At, B1); G_BAR;
;       G_LDA(At, 0, 1); G_STAGE(G_SA(0, 0), a2, voffA);
;       G_BAR; G_WAIT_L(0); G_MMA(1, 0, At, B0); G_BAR; G_SCHED;
;       G_STAGE(G_SB(0, 1), b2 + hstepB, voffB);
;       G_WAIT_V(6); G_BAR; G_MMA(1, 1, At, B1); G_BAR;
.LBB0_282:
	s_add_i32 s1, s84, 0x100
	ds_read_b128 v[134:137], v208
	ds_read_b128 v[138:141], v208 offset:1024
	ds_read_b128 v[152:155], v208 offset:2048
	ds_read_b128 v[156:159], v208 offset:3072
	s_add_u32 s10, s9, s0
	s_addc_u32 s11, s19, 0
	s_add_i32 m0, s15, 0xc000
	ds_read_b128 v[160:163], v151
	ds_read_b128 v[164:167], v151 offset:1024
	ds_read_b128 v[168:171], v151 offset:2048
	ds_read_b128 v[172:175], v151 offset:3072
	ds_read_b128 v[176:179], v151 offset:4096
	ds_read_b128 v[180:183], v151 offset:5120
	ds_read_b128 v[184:187], v151 offset:6144
	ds_read_b128 v[188:191], v151 offset:7168
	global_load_lds_dwordx4 v128, s[10:11]
	s_add_i32 m0, s15, 0xe000
	s_nop 0
	global_load_lds_dwordx4 v130, s[10:11]
	s_waitcnt lgkmcnt(8)
	s_barrier
	s_waitcnt lgkmcnt(0)
	v_mfma_f32_16x16x32_bf16 v[124:127], v[134:137], v[160:163], v[124:127]
	v_mfma_f32_16x16x32_bf16 v[120:123], v[152:155], v[160:163], v[120:123]
	v_mfma_f32_16x16x32_bf16 v[108:111], v[134:137], v[168:171], v[108:111]
	v_mfma_f32_16x16x32_bf16 v[104:107], v[152:155], v[168:171], v[104:107]
	v_mfma_f32_16x16x32_bf16 v[92:95], v[134:137], v[176:179], v[92:95]
	v_mfma_f32_16x16x32_bf16 v[88:91], v[152:155], v[176:179], v[88:91]
	v_mfma_f32_16x16x32_bf16 v[76:79], v[134:137], v[184:187], v[76:79]
	v_mfma_f32_16x16x32_bf16 v[72:75], v[152:155], v[184:187], v[72:75]
	v_mfma_f32_16x16x32_bf16 v[124:127], v[138:141], v[164:167], v[124:127]
	v_mfma_f32_16x16x32_bf16 v[120:123], v[156:159], v[164:167], v[120:123]
	v_mfma_f32_16x16x32_bf16 v[108:111], v[138:141], v[172:175], v[108:111]
	v_mfma_f32_16x16x32_bf16 v[104:107], v[156:159], v[172:175], v[104:107]
	v_mfma_f32_16x16x32_bf16 v[92:95], v[138:141], v[180:183], v[92:95]
	v_mfma_f32_16x16x32_bf16 v[88:91], v[156:159], v[180:183], v[88:91]
	v_mfma_f32_16x16x32_bf16 v[76:79], v[138:141], v[188:191], v[76:79]
	v_mfma_f32_16x16x32_bf16 v[72:75], v[156:159], v[188:191], v[72:75]
	s_barrier
	s_add_i32 s0, s85, 0x100
	s_add_i32 s1, s1, s5
	ds_read_b128 v[192:195], v208 offset:16384
	ds_read_b128 v[196:199], v208 offset:17408
	ds_read_b128 v[200:203], v208 offset:18432
	ds_read_b128 v[204:207], v208 offset:19456
	s_mov_b32 m0, s1
	s_nop 0
	global_load_lds_dwordx4 v146, s[76:77]
	s_add_i32 m0, s1, 0x2000
	s_nop 0
	global_load_lds_dwordx4 v132, s[76:77]
	s_barrier
	s_waitcnt lgkmcnt(0)
	v_mfma_f32_16x16x32_bf16 v[116:119], v[192:195], v[160:163], v[116:119]
	v_mfma_f32_16x16x32_bf16 v[112:115], v[200:203], v[160:163], v[112:115]
	v_mfma_f32_16x16x32_bf16 v[100:103], v[192:195], v[168:171], v[100:103]
	v_mfma_f32_16x16x32_bf16 v[96:99], v[200:203], v[168:171], v[96:99]
	v_mfma_f32_16x16x32_bf16 v[84:87], v[192:195], v[176:179], v[84:87]
	v_mfma_f32_16x16x32_bf16 v[80:83], v[200:203], v[176:179], v[80:83]
	v_mfma_f32_16x16x32_bf16 v[68:71], v[192:195], v[184:187], v[68:71]
	v_mfma_f32_16x16x32_bf16 v[64:67], v[200:203], v[184:187], v[64:67]
	v_mfma_f32_16x16x32_bf16 v[116:119], v[196:199], v[164:167], v[116:119]
	v_mfma_f32_16x16x32_bf16 v[112:115], v[204:207], v[164:167], v[112:115]
	v_mfma_f32_16x16x32_bf16 v[100:103], v[196:199], v[172:175], v[100:103]
	v_mfma_f32_16x16x32_bf16 v[96:99], v[204:207], v[172:175], v[96:99]
	v_mfma_f32_16x16x32_bf16 v[84:87], v[196:199], v[180:183], v[84:87]
	v_mfma_f32_16x16x32_bf16 v[80:83], v[204:207], v[180:183], v[80:83]
	v_mfma_f32_16x16x32_bf16 v[68:71], v[196:199], v[188:191], v[68:71]
	v_mfma_f32_16x16x32_bf16 v[64:67], v[204:207], v[188:191], v[64:67]
	s_mov_b32 m0, s15
	s_barrier
	ds_read_b128 v[160:163], v151 offset:16384
	ds_read_b128 v[164:167], v151 offset:17408
	ds_read_b128 v[168:171], v151 offset:18432
	ds_read_b128 v[172:175], v151 offset:19456
	ds_read_b128 v[176:179], v151 offset:20480
	ds_read_b128 v[180:183], v151 offset:21504
	ds_read_b128 v[184:187], v151 offset:22528
	ds_read_b128 v[188:191], v151 offset:23552
	global_load_lds_dwordx4 v128, s[74:75]
	s_mov_b32 m0, s24
	s_nop 0
	global_load_lds_dwordx4 v130, s[74:75]
	s_barrier
	s_waitcnt lgkmcnt(0)
	v_mfma_f32_16x16x32_bf16 v[60:63], v[134:137], v[160:163], v[60:63]
	v_mfma_f32_16x16x32_bf16 v[56:59], v[152:155], v[160:163], v[56:59]
	v_mfma_f32_16x16x32_bf16 v[44:47], v[134:137], v[168:171], v[44:47]
	v_mfma_f32_16x16x32_bf16 v[40:43], v[152:155], v[168:171], v[40:43]
	v_mfma_f32_16x16x32_bf16 v[28:31], v[134:137], v[176:179], v[28:31]
	v_mfma_f32_16x16x32_bf16 v[24:27], v[152:155], v[176:179], v[24:27]
	v_mfma_f32_16x16x32_bf16 v[12:15], v[134:137], v[184:187], v[12:15]
	v_mfma_f32_16x16x32_bf16 v[8:11], v[152:155], v[184:187], v[8:11]
	v_mfma_f32_16x16x32_bf16 v[60:63], v[138:141], v[164:167], v[60:63]
	v_mfma_f32_16x16x32_bf16 v[56:59], v[156:159], v[164:167], v[56:59]
	v_mfma_f32_16x16x32_bf16 v[44:47], v[138:141], v[172:175], v[44:47]
	v_mfma_f32_16x16x32_bf16 v[40:43], v[156:159], v[172:175], v[40:43]
	v_mfma_f32_16x16x32_bf16 v[28:31], v[138:141], v[180:183], v[28:31]
	v_mfma_f32_16x16x32_bf16 v[24:27], v[156:159], v[180:183], v[24:27]
	v_mfma_f32_16x16x32_bf16 v[12:15], v[138:141], v[188:191], v[12:15]
	v_mfma_f32_16x16x32_bf16 v[8:11], v[156:159], v[188:191], v[8:11]
	s_barrier
	s_add_u32 s10, s76, 0x80000
	s_addc_u32 s11, s77, 0
	s_add_i32 s0, s0, s5
	s_mov_b32 m0, s0
	s_nop 0
	global_load_lds_dwordx4 v146, s[10:11]
	s_add_i32 m0, s0, 0x2000
	s_nop 0
	global_load_lds_dwordx4 v132, s[10:11]
	s_waitcnt vmcnt(6)
	s_barrier
; #define G_STAGE(bufoff, gbase, voff) do { _Pragma("unroll") for (int _i = 0; _i < 2; ++_i) \
;         __builtin_amdgcn_global_load_lds((const unsigned*)((const char*)(gbase) + (voff)[_i]), (LAS unsigned*)(lds + (bufoff) + ldsw + _i * 8192), 16, 0, 0); } while (0)
; #define G_LDA(dst, b, h) do { _Pragma("unroll") for (int m = 0; m < 4; ++m) _Pragma("unroll") for (int k = 0; k < 2; ++k) dst[m][k] = *(const LAS bf16x8*)(lds + G_SA(b, h) + aoff + m * 2048 + k * 1024); } while (0)
; #define G_LDB(dst, b, h) do { _Pragma("unroll") for (int n = 0; n < 2; ++n) _Pragma("unroll") for (int k = 0; k < 2; ++k) dst[n][k] = *(const LAS bf16x8*)(lds + G_SB(b, h) + boff + n * 2048 + k * 1024); } while (0)
; #define G_MMA(ai, bj, At, Bt) do { __builtin_amdgcn_s_setprio(1); _Pragma("unroll") for (int m = 0; m < 4; ++m) _Pragma("unroll") for (int n = 0; n < 2; ++n) _Pragma("unroll") for (int k = 0; k < 2; ++k) \
;         acc[ai][bj][m][n] = __builtin_amdgcn_mfma_f32_16x16x32_bf16(Bt[n][k], At[m][k], acc[ai][bj][m][n], 0, 0, 0); __builtin_amdgcn_s_setprio(0); } while (0)
; #define G_WAIT_V(n) asm volatile("s_waitcnt vmcnt(" #n ")" ::: "memory")
; #define G_WAIT_L(n) asm volatile("s_waitcnt lgkmcnt(" #n ")" ::: "memory")
; #define G_BAR __builtin_amdgcn_s_barrier()
; #define G_SCHED __builtin_amdgcn_sched_barrier(0)
; template <class J>
; DI void gemm_phase(LAS unsigned char* lds, const J& job) {
;     ...
;       G_WAIT_V(6); G_BAR; G_MMA(1, 1, At, B1); G_BAR;
;       G_LDB(B0, 1, 0); G_SCHED; G_LDA(At, 1, 0); G_STAGE(G_SA(0, 1), a2 + hstepA, voffA);
;       G_WAIT_L(8); G_BAR; G_WAIT_L(0); G_MMA(0, 0, At, B0); G_BAR; G_SCHED;
;       G_LDB(B1, 1, 1); G_STAGE(G_SB(1, 0), b3, voffB);
;       G_BAR; G_WAIT_L(0); G_MMA(0, 1, At, B1); G_BAR;
;       G_LDA(At, 1, 1); G_STAGE(G_SA(1, 0), a3, voffA);
;       G_BAR; G_WAIT_L(0); G_MMA(1, 0, At, B0); G_BAR; G_SCHED;
	v_mfma_f32_16x16x32_bf16 v[52:55], v[192:195], v[160:163], v[52:55]
	v_mfma_f32_16x16x32_bf16 v[48:51], v[200:203], v[160:163], v[48:51]
	v_mfma_f32_16x16x32_bf16 v[36:39], v[192:195], v[168:171], v[36:39]
	v_mfma_f32_16x16x32_bf16 v[32:35], v[200:203], v[168:171], v[32:35]
	v_mfma_f32_16x16x32_bf16 v[20:23], v[192:195], v[176:179], v[20:23]
	v_mfma_f32_16x16x32_bf16 v[16:19], v[200:203], v[176:179], v[16:19]
	v_mfma_f32_16x16x32_bf16 v[4:7], v[192:195], v[184:187], v[4:7]
	v_mfma_f32_16x16x32_bf16 v[0:3], v[200:203], v[184:187], v[0:3]
	v_mfma_f32_16x16x32_bf16 v[52:55], v[196:199], v[164:167], v[52:55]
	v_mfma_f32_16x16x32_bf16 v[48:51], v[204:207], v[164:167], v[48:51]
	v_mfma_f32_16x16x32_bf16 v[36:39], v[196:199], v[172:175], v[36:39]
	v_mfma_f32_16x16x32_bf16 v[32:35], v[204:207], v[172:175], v[32:35]
	v_mfma_f32_16x16x32_bf16 v[20:23], v[196:199], v[180:183], v[20:23]
	v_mfma_f32_16x16x32_bf16 v[16:19], v[204:207], v[180:183], v[16:19]
	v_mfma_f32_16x16x32_bf16 v[4:7], v[196:199], v[188:191], v[4:7]
	v_mfma_f32_16x16x32_bf16 v[0:3], v[204:207], v[188:191], v[0:3]
	s_add_i32 s0, s88, 0x100
	s_barrier
	ds_read_b128 v[134:137], v208 offset:32768
	ds_read_b128 v[138:141], v208 offset:33792
	ds_read_b128 v[152:155], v208 offset:34816
	ds_read_b128 v[156:159], v208 offset:35840
	s_add_u32 s10, s74, 0x80000
	s_addc_u32 s11, s75, 0
	s_mov_b32 m0, s25
	ds_read_b128 v[160:163], v151 offset:32768
	ds_read_b128 v[164:167], v151 offset:33792
	ds_read_b128 v[168:171], v151 offset:34816
	ds_read_b128 v[172:175], v151 offset:35840
	ds_read_b128 v[176:179], v151 offset:36864
	ds_read_b128 v[180:183], v151 offset:37888
	ds_read_b128 v[184:187], v151 offset:38912
	ds_read_b128 v[188:191], v151 offset:39936
	global_load_lds_dwordx4 v128, s[10:11]
	s_mov_b32 m0, s36
	s_nop 0
	global_load_lds_dwordx4 v130, s[10:11]
	s_waitcnt lgkmcnt(8)
	s_barrier
	s_waitcnt lgkmcnt(0)
	v_mfma_f32_16x16x32_bf16 v[124:127], v[134:137], v[160:163], v[124:127]
	v_mfma_f32_16x16x32_bf16 v[120:123], v[152:155], v[160:163], v[120:123]
	v_mfma_f32_16x16x32_bf16 v[108:111], v[134:137], v[168:171], v[108:111]
	v_mfma_f32_16x16x32_bf16 v[104:107], v[152:155], v[168:171], v[104:107]
	v_mfma_f32_16x16x32_bf16 v[92:95], v[134:137], v[176:179], v[92:95]
	v_mfma_f32_16x16x32_bf16 v[88:91], v[152:155], v[176:179], v[88:91]
	v_mfma_f32_16x16x32_bf16 v[76:79], v[134:137], v[184:187], v[76:79]
	v_mfma_f32_16x16x32_bf16 v[72:75], v[152:155], v[184:187], v[72:75]
	v_mfma_f32_16x16x32_bf16 v[124:127], v[138:141], v[164:167], v[124:127]
	v_mfma_f32_16x16x32_bf16 v[120:123], v[156:159], v[164:167], v[120:123]
	v_mfma_f32_16x16x32_bf16 v[108:111], v[138:141], v[172:175], v[108:111]
	v_mfma_f32_16x16x32_bf16 v[104:107], v[156:159], v[172:175], v[104:107]
	v_mfma_f32_16x16x32_bf16 v[92:95], v[138:141], v[180:183], v[92:95]
	v_mfma_f32_16x16x32_bf16 v[88:91], v[156:159], v[180:183], v[88:91]
	v_mfma_f32_16x16x32_bf16 v[76:79], v[138:141], v[188:191], v[76:79]
	v_mfma_f32_16x16x32_bf16 v[72:75], v[156:159], v[188:191], v[72:75]
	s_barrier
	s_add_i32 s1, s89, 0x100
	s_add_i32 s0, s0, s5
	ds_read_b128 v[192:195], v208 offset:49152
	ds_read_b128 v[196:199], v208 offset:50176
	ds_read_b128 v[200:203], v208 offset:51200
	ds_read_b128 v[204:207], v208 offset:52224
	s_mov_b32 m0, s0
	s_nop 0
	global_load_lds_dwordx4 v146, s[70:71]
	s_add_i32 m0, s0, 0x2000
	s_nop 0
	global_load_lds_dwordx4 v132, s[70:71]
	s_barrier
	s_waitcnt lgkmcnt(0)
	v_mfma_f32_16x16x32_bf16 v[116:119], v[192:195], v[160:163], v[116:119]
	v_mfma_f32_16x16x32_bf16 v[112:115], v[200:203], v[160:163], v[112:115]
	v_mfma_f32_16x16x32_bf16 v[100:103], v[192:195], v[168:171], v[100:103]
	v_mfma_f32_16x16x32_bf16 v[96:99], v[200:203], v[168:171], v[96:99]
	v_mfma_f32_16x16x32_bf16 v[84:87], v[192:195], v[176:179], v[84:87]
	v_mfma_f32_16x16x32_bf16 v[80:83], v[200:203], v[176:179], v[80:83]
	v_mfma_f32_16x16x32_bf16 v[68:71], v[192:195], v[184:187], v[68:71]
	v_mfma_f32_16x16x32_bf16 v[64:67], v[200:203], v[184:187], v[64:67]
	v_mfma_f32_16x16x32_bf16 v[116:119], v[196:199], v[164:167], v[116:119]
	v_mfma_f32_16x16x32_bf16 v[112:115], v[204:207], v[164:167], v[112:115]
	v_mfma_f32_16x16x32_bf16 v[100:103], v[196:199], v[172:175], v[100:103]
	v_mfma_f32_16x16x32_bf16 v[96:99], v[204:207], v[172:175], v[96:99]
	v_mfma_f32_16x16x32_bf16 v[84:87], v[196:199], v[180:183], v[84:87]
	v_mfma_f32_16x16x32_bf16 v[80:83], v[204:207], v[180:183], v[80:83]
	v_mfma_f32_16x16x32_bf16 v[68:71], v[196:199], v[188:191], v[68:71]
	v_mfma_f32_16x16x32_bf16 v[64:67], v[204:207], v[188:191], v[64:67]
	s_mov_b32 m0, s45
	s_barrier
; template <class J>
; DI void gemm_phase(LAS unsigned char* lds, const J& job) {
;     ...
;       const bool last = (t == nt - 2);
;       const char* a1 = cA + G_KT(t + 1);
;       const char* a2 = last ? nA + G_KT(0) : cA + G_KT(t + 2); const char* b2 = last ? nB + G_KT(0) : cB + G_KT(t + 2);
;       const char* a3 = last ? nA + G_KT(1) : cA + G_KT(t + 3); const char* b3 = last ? nB + G_KT(1) : cB + G_KT(t + 3);
;       G_LDB(B0, 0, 0); G_SCHED; G_LDA(At, 0, 0); G_STAGE(G_SA(1, 1), a1 + hstepA, voffA);
;       G_WAIT_L(8); G_BAR; G_WAIT_L(0); G_MMA(0, 0, At, B0); G_BAR; G_SCHED;
;       G_LDB(B1, 0, 1); G_STAGE(G_SB(0, 0), b2, voffB);
;       G_BAR; G_WAIT_L(0); G_MMA(0, 1, At, B1); G_BAR;
;       G_LDA(At, 0, 1); G_STAGE(G_SA(0, 0), a2, voffA);
;       G_BAR; G_WAIT_L(0); G_MMA(1, 0, At, B0); G_BAR; G_SCHED;
;       G_STAGE(G_SB(0, 1), b2 + hstepB, voffB);
;       G_WAIT_V(6); G_BAR; G_MMA(1, 1, At, B1); G_BAR;
;       G_LDB(B0, 1, 0); G_SCHED; G_LDA(At, 1, 0); G_STAGE(G_SA(0, 1), a2 + hstepA, voffA);
;       G_WAIT_L(8); G_BAR; G_WAIT_L(0); G_MMA(0, 0, At, B0); G_BAR; G_SCHED;
;       G_LDB(B1, 1, 1); G_STAGE(G_SB(1, 0), b3, voffB);
;       G_BAR; G_WAIT_L(0); G_MMA(0, 1, At, B1); G_BAR;
;       G_LDA(At, 1, 1); G_STAGE(G_SA(1, 0), a3, voffA);
;       G_BAR; G_WAIT_L(0); G_MMA(1, 0, At, B0); G_BAR; G_SCHED;
;       G_STAGE(G_SB(1, 1), b3 + hstepB, voffB);
;       G_WAIT_V(6); G_BAR; G_MMA(1, 1, At, B1); G_BAR;
;   DI void epi(const Acc& acc, const Unit& u, int wr, int wc, int fr, int fq) const {
; #pragma unroll
;     for (int ai = 0; ai < 2; ++ai)
; #pragma unroll
;       for (int m = 0; m < 4; ++m) {
;         const int rl = ai * HALF + wr * 64 + m * 16 + fr;
; #pragma unroll
;         for (int bj = 0; bj < 2; ++bj) {
;           const int col = u.pn * 256 + bj * HALF + wc * 32 + 8 * fq;
;           const f32x4 v0 = acc[ai][bj][m][0], v1 = acc[ai][bj][m][1];
;           const int row = u.pm * 256 + rl;
;           u32x4 o; o.x = pk2(v0.x, v0.y); o.y = pk2(v0.z, v0.w); o.z = pk2(v1.x, v1.y); o.w = pk2(v1.z, v1.w);
;           *(u32x4*)(proj + (size_t)row * NPROJ + col) = o;
;           if (u.pn >= 8 && u.pn < 12) {
;             const int isv = u.pn >= 10; const int cc = col - (isv ? C_BV : C_BK);
;             float* dst = out + (isv ? O_VP : O_KP) + ((size_t)l * TP + row) * 512 + cc;
;             *(f32x4*)dst = v0; *(f32x4*)(dst + 4) = v1;
	ds_read_b128 v[160:163], v151 offset:49152
	ds_read_b128 v[164:167], v151 offset:50176
	ds_read_b128 v[168:171], v151 offset:51200
	ds_read_b128 v[172:175], v151 offset:52224
	ds_read_b128 v[176:179], v151 offset:53248
	ds_read_b128 v[180:183], v151 offset:54272
	ds_read_b128 v[184:187], v151 offset:55296
	ds_read_b128 v[188:191], v151 offset:56320
	global_load_lds_dwordx4 v128, s[72:73]
	s_mov_b32 m0, s65
	s_nop 0
	global_load_lds_dwordx4 v130, s[72:73]
	s_barrier
	s_waitcnt lgkmcnt(0)
	v_mfma_f32_16x16x32_bf16 v[60:63], v[134:137], v[160:163], v[60:63]
	v_mfma_f32_16x16x32_bf16 v[56:59], v[152:155], v[160:163], v[56:59]
	v_mfma_f32_16x16x32_bf16 v[44:47], v[134:137], v[168:171], v[44:47]
	v_mfma_f32_16x16x32_bf16 v[40:43], v[152:155], v[168:171], v[40:43]
	v_mfma_f32_16x16x32_bf16 v[28:31], v[134:137], v[176:179], v[28:31]
	v_mfma_f32_16x16x32_bf16 v[24:27], v[152:155], v[176:179], v[24:27]
	v_mfma_f32_16x16x32_bf16 v[12:15], v[134:137], v[184:187], v[12:15]
	v_mfma_f32_16x16x32_bf16 v[8:11], v[152:155], v[184:187], v[8:11]
	v_mfma_f32_16x16x32_bf16 v[60:63], v[138:141], v[164:167], v[60:63]
	v_mfma_f32_16x16x32_bf16 v[56:59], v[156:159], v[164:167], v[56:59]
	v_mfma_f32_16x16x32_bf16 v[44:47], v[138:141], v[172:175], v[44:47]
	v_mfma_f32_16x16x32_bf16 v[40:43], v[156:159], v[172:175], v[40:43]
	v_mfma_f32_16x16x32_bf16 v[28:31], v[138:141], v[180:183], v[28:31]
	v_mfma_f32_16x16x32_bf16 v[24:27], v[156:159], v[180:183], v[24:27]
	v_mfma_f32_16x16x32_bf16 v[12:15], v[138:141], v[188:191], v[12:15]
	v_mfma_f32_16x16x32_bf16 v[8:11], v[156:159], v[188:191], v[8:11]
	s_barrier
	s_add_u32 s10, s70, 0x80000
	s_addc_u32 s11, s71, 0
	s_add_i32 s0, s1, s5
	s_mov_b32 m0, s0
	s_nop 0
	global_load_lds_dwordx4 v146, s[10:11]
	s_add_i32 m0, s0, 0x2000
	s_nop 0
	global_load_lds_dwordx4 v132, s[10:11]
	s_add_i32 s6, s6, 2
	s_addk_i32 s56, 0x100
	s_addk_i32 s7, 0x100
	s_add_i32 s1, s56, 0xffffff80
	s_and_b32 s0, s7, 0xf80
	s_and_b32 s1, s1, 0xf00
	s_add_u32 s10, s68, s1
	s_addc_u32 s11, s69, 0
	s_add_u32 s1, s66, s1
	s_addc_u32 s57, s67, 0
	s_and_b32 s70, s56, 0xf80
	s_add_u32 s71, s68, s70
	s_addc_u32 s72, s69, 0
	s_add_u32 s70, s66, s70
	s_addc_u32 s80, s67, 0
	s_cmp_eq_u32 s6, 28
	s_cselect_b32 s75, s46, s11
	s_cselect_b32 s74, s21, s10
	s_cselect_b32 s77, s96, s57
	s_cselect_b32 s76, s47, s1
	s_cselect_b32 s73, s97, s72
	s_cselect_b32 s72, s33, s71
	s_cselect_b32 s71, vcc_hi, s80
	s_cselect_b32 s70, vcc_lo, s70
	s_waitcnt vmcnt(6)
	s_barrier
	v_mfma_f32_16x16x32_bf16 v[52:55], v[192:195], v[160:163], v[52:55]
	v_mfma_f32_16x16x32_bf16 v[48:51], v[200:203], v[160:163], v[48:51]
	v_mfma_f32_16x16x32_bf16 v[36:39], v[192:195], v[168:171], v[36:39]
	v_mfma_f32_16x16x32_bf16 v[32:35], v[200:203], v[168:171], v[32:35]
	v_mfma_f32_16x16x32_bf16 v[20:23], v[192:195], v[176:179], v[20:23]
	v_mfma_f32_16x16x32_bf16 v[16:19], v[200:203], v[176:179], v[16:19]
	v_mfma_f32_16x16x32_bf16 v[4:7], v[192:195], v[184:187], v[4:7]
	v_mfma_f32_16x16x32_bf16 v[0:3], v[200:203], v[184:187], v[0:3]
	v_mfma_f32_16x16x32_bf16 v[52:55], v[196:199], v[164:167], v[52:55]
	v_mfma_f32_16x16x32_bf16 v[48:51], v[204:207], v[164:167], v[48:51]
	v_mfma_f32_16x16x32_bf16 v[36:39], v[196:199], v[172:175], v[36:39]
	v_mfma_f32_16x16x32_bf16 v[32:35], v[204:207], v[172:175], v[32:35]
	v_mfma_f32_16x16x32_bf16 v[20:23], v[196:199], v[180:183], v[20:23]
	v_mfma_f32_16x16x32_bf16 v[16:19], v[204:207], v[180:183], v[16:19]
	v_mfma_f32_16x16x32_bf16 v[4:7], v[196:199], v[188:191], v[4:7]
	v_mfma_f32_16x16x32_bf16 v[0:3], v[204:207], v[188:191], v[0:3]
	s_cmp_gt_u32 s6, 29
	s_barrier
	s_cbranch_scc0 .LBB0_282
	v_mov_b32_e32 v135, v148
	v_mov_b32_e32 v134, v149
	s_lshl_b32 s0, s64, 8
	s_or_b32 s0, s0, s38
	v_lshl_add_u32 v134, v134, 3, s0
	s_lshl_b32 s0, s8, 8
	s_add_i32 s0, s0, s37
	v_add_u32_e32 v136, s0, v135
	s_and_b32 s0, s64, -4
	s_cmp_eq_u32 s0, 8
	s_cselect_b64 s[66:67], -1, 0
	s_cmp_gt_u32 s64, 9
	s_cselect_b64 s[6:7], -1, 0
	s_and_b64 s[6:7], s[6:7], exec
	s_movk_i32 s1, 0xf600
	v_mov_b64_e32 v[138:139], s[26:27]
	s_cselect_b32 s7, s1, 0xfffff800
	s_mov_b32 s1, 0x3040000
	v_ashrrev_i32_e32 v137, 31, v136
	v_mad_i64_i32 v[138:139], s[8:9], v136, s92, v[138:139]
	v_ashrrev_i32_e32 v135, 31, v134
	s_cselect_b32 s6, s1, 0x2040000
	s_cmp_lg_u32 s0, 8
	v_lshlrev_b64 v[140:141], 11, v[136:137]
	v_lshl_add_u64 v[142:143], v[134:135], 1, v[138:139]
	v_add_u32_e32 v138, s7, v134
	v_cvt_pk_bf16_f32 v152, v124, v125
	v_cvt_pk_bf16_f32 v153, v126, v127
	v_cvt_pk_bf16_f32 v154, v120, v121
	v_cvt_pk_bf16_f32 v155, v122, v123
	global_store_dwordx4 v[142:143], v[152:155], off
	s_cbranch_scc1 .LBB0_285
	s_lshl_b32 s0, s6, 2
	s_add_u32 s8, s83, s0
	s_addc_u32 s9, s86, 0
	v_lshl_add_u64 v[152:153], s[8:9], 0, v[140:141]
	v_ashrrev_i32_e32 v139, 31, v138
	v_lshl_add_u64 v[152:153], v[138:139], 2, v[152:153]
	global_store_dwordx4 v[152:153], v[124:127], off
	global_store_dwordx4 v[152:153], v[120:123], off offset:16
